# epilogue de-serialisation: second-half residual tile loads hoisted next to the first-half loads in FFN1-down, xattn-out, FFN2-down epilogues (wait once)
# speedup vs baseline: 1.0060x; 1.0035x over previous
; __device__ __forceinline__ u32x4 pack8(f32x4 a, f32x4 b) { u32x4 w; w.x = cvtpk(a[0], a[1]); w.y = cvtpk(a[2], a[3]); w.z = cvtpk(b[0], b[1]); w.w = cvtpk(b[2], b[3]); return w; }
;     __device__ __forceinline__ void operator()(AccRef acc, const Unit& u, int wr, int wc, int fr, int fq) const {
; #pragma unroll
;         for (int ai = 0; ai < 2; ++ai) {
;             u32x4 ow[4][2];
; #pragma unroll
;             for (int m = 0; m < 4; ++m)
; #pragma unroll
;                 for (int bj = 0; bj < 2; ++bj)
;                     ow[m][bj] = *(const u32x4*)(hb + (size_t)(u.pm * 256 + ai * 128 + wr * 64 + m * 16 + fr) * D + u.pn * 256 + bj * 128 + wc * 32 + 8 * fq);
;             __builtin_amdgcn_sched_barrier(0);
; #pragma unroll
;             for (int m = 0; m < 4; ++m) {
;                 const int row = u.pm * 256 + ai * 128 + wr * 64 + m * 16 + fr; float part = 0.f;
;                 const float sc = RS ? scale * rst[u.ui * 256 + ai * 128 + wr * 64 + m * 16 + fr] : scale;
; #pragma unroll
;                 for (int bj = 0; bj < 2; ++bj) {
;                     const size_t idx = (size_t)row * D + u.pn * 256 + bj * 128 + wc * 32 + 8 * fq;
;                     const u32x4 o4 = ow[m][bj];
;                     f32x4 v0, v1;
;                     v0[0] = __uint_as_float(o4.x << 16); v0[1] = __uint_as_float(o4.x & 0xffff0000u); v0[2] = __uint_as_float(o4.y << 16); v0[3] = __uint_as_float(o4.y & 0xffff0000u);
;                     v1[0] = __uint_as_float(o4.z << 16); v1[1] = __uint_as_float(o4.z & 0xffff0000u); v1[2] = __uint_as_float(o4.w << 16); v1[3] = __uint_as_float(o4.w & 0xffff0000u);
;                     v0 = v0 + acc[ai][bj][m][0] * sc; v1 = v1 + acc[ai][bj][m][1] * sc;
;                     *(u32x4*)(hb + idx) = pack8(v0, v1);
;                     part += (v0[0] * v0[0] + v0[1] * v0[1]) + (v0[2] * v0[2] + v0[3] * v0[3]) + (v1[0] * v1[0] + v1[1] * v1[1]) + (v1[2] * v1[2] + v1[3] * v1[3]);
;                 }
;                 part = fq_sum(part);
;                 if (fq == 0) ssn[(size_t)row * 16 + u.pn * 4 + wc] = part;
.LBB0_610:
	s_lshl_b32 s60, s75, 8
	s_lshl_b32 s17, s76, 8
	s_ashr_i32 s61, s60, 31
	s_lshl_b32 s58, s75, 2
	v_mov_b32_e32 v0, v236
	s_add_i32 s17, s17, s46
	s_ashr_i32 s59, s58, 31
	s_lshl_b64 s[62:63], s[60:61], 1
	s_add_u32 s76, s70, s62
	v_bfe_u32 v170, v0, 4, 2
	v_and_or_b32 v154, v0, 15, s17
	s_addc_u32 s77, s71, s63
	v_lshlrev_b32_e32 v0, 4, v170
	v_ashrrev_i32_e32 v155, 31, v154
	v_or_b32_e32 v166, 16, v154
	v_lshl_add_u64 v[156:157], s[76:77], 0, v[0:1]
	v_lshlrev_b64 v[180:181], 11, v[154:155]
	v_ashrrev_i32_e32 v167, 31, v166
	v_or_b32_e32 v162, 32, v154
	v_lshl_add_u64 v[130:131], v[156:157], 0, v[180:181]
	v_lshlrev_b64 v[168:169], 11, v[166:167]
	v_ashrrev_i32_e32 v163, 31, v162
	v_or_b32_e32 v158, 48, v154
	global_load_dwordx4 v[172:175], v[130:131], off
	global_load_dwordx4 v[176:179], v[130:131], off offset:256
	v_lshl_add_u64 v[130:131], v[156:157], 0, v[168:169]
	v_lshlrev_b64 v[164:165], 11, v[162:163]
	v_ashrrev_i32_e32 v159, 31, v158
	global_load_dwordx4 v[150:153], v[130:131], off
	global_load_dwordx4 v[146:149], v[130:131], off offset:256
	v_lshl_add_u64 v[130:131], v[156:157], 0, v[164:165]
	v_lshlrev_b64 v[160:161], 11, v[158:159]
	global_load_dwordx4 v[142:145], v[130:131], off
	global_load_dwordx4 v[138:141], v[130:131], off offset:256
	v_lshl_add_u64 v[130:131], v[156:157], 0, v[160:161]
	global_load_dwordx4 v[134:137], v[130:131], off
	s_nop 0
	global_load_dwordx4 v[130:133], v[130:131], off offset:256
	v_mov_b32_e32 v220, 0x40000
	v_mov_b32_e32 v221, 0
	v_lshl_add_u64 v[222:223], v[220:221], 0, v[180:181]
	v_lshl_add_u64 v[222:223], v[156:157], 0, v[222:223]
	global_load_dwordx4 v[196:199], v[222:223], off
	global_load_dwordx4 v[200:203], v[222:223], off offset:256
	v_lshl_add_u64 v[222:223], v[220:221], 0, v[168:169]
	v_lshl_add_u64 v[222:223], v[156:157], 0, v[222:223]
	global_load_dwordx4 v[206:209], v[222:223], off
	global_load_dwordx4 v[210:213], v[222:223], off offset:256
	v_lshl_add_u64 v[222:223], v[220:221], 0, v[164:165]
	v_lshl_add_u64 v[222:223], v[156:157], 0, v[222:223]
	global_load_dwordx4 v[238:241], v[222:223], off
	global_load_dwordx4 v[242:245], v[222:223], off offset:256
	v_lshl_add_u64 v[222:223], v[220:221], 0, v[160:161]
	v_lshl_add_u64 v[222:223], v[156:157], 0, v[222:223]
	global_load_dwordx4 v[246:249], v[222:223], off
	global_load_dwordx4 v[250:253], v[222:223], off offset:256
	v_cmp_eq_u32_e32 vcc, 0, v170
	v_lshl_add_u64 v[180:181], s[10:11], 0, v[180:181]
	s_waitcnt vmcnt(0)
	v_lshlrev_b32_e32 v182, 16, v172
	v_and_b32_e32 v183, 0xffff0000, v172
	v_lshlrev_b32_e32 v172, 16, v173
	v_and_b32_e32 v173, 0xffff0000, v173
	v_lshlrev_b32_e32 v184, 16, v174
	v_and_b32_e32 v185, 0xffff0000, v174
	v_lshlrev_b32_e32 v174, 16, v175
	v_and_b32_e32 v175, 0xffff0000, v175
	v_lshl_add_u64 v[180:181], v[180:181], 0, s[62:63]
	s_lshl_b32 s18, s49, 1
	v_pk_fma_f32 v[128:129], v[128:129], 0.5, v[172:173] op_sel_hi:[1,0,1]
	v_pk_fma_f32 v[126:127], v[126:127], 0.5, v[182:183] op_sel_hi:[1,0,1]
	v_pk_fma_f32 v[172:173], v[124:125], 0.5, v[174:175] op_sel_hi:[1,0,1]
	v_pk_fma_f32 v[174:175], v[122:123], 0.5, v[184:185] op_sel_hi:[1,0,1]
	v_lshl_add_u64 v[180:181], v[180:181], 0, s[18:19]
	v_cvt_pk_bf16_f32 v122, v126, v127
	v_cvt_pk_bf16_f32 v123, v128, v129
	v_cvt_pk_bf16_f32 v124, v174, v175
	v_cvt_pk_bf16_f32 v125, v172, v173
	v_lshl_add_u64 v[180:181], v[180:181], 0, v[0:1]
	global_store_dwordx4 v[180:181], v[122:125], off
	v_mul_f32_e32 v0, v127, v127
	v_fmac_f32_e32 v0, v126, v126
	v_mul_f32_e32 v122, v129, v129
	v_fmac_f32_e32 v122, v128, v128
	v_add_f32_e32 v0, v0, v122
	v_mul_f32_e32 v122, v175, v175
	v_fmac_f32_e32 v122, v174, v174
	v_add_f32_e32 v0, v122, v0
	v_mul_f32_e32 v122, v173, v173
	v_fmac_f32_e32 v122, v172, v172
	v_add_f32_e32 v0, v122, v0
	v_lshlrev_b32_e32 v122, 16, v176
	v_and_b32_e32 v123, 0xffff0000, v176
	v_lshlrev_b32_e32 v124, 16, v177
	v_and_b32_e32 v125, 0xffff0000, v177
	v_lshlrev_b32_e32 v126, 16, v178
	v_and_b32_e32 v127, 0xffff0000, v178
	v_lshlrev_b32_e32 v128, 16, v179
	v_and_b32_e32 v129, 0xffff0000, v179
	v_pk_fma_f32 v[120:121], v[120:121], 0.5, v[124:125] op_sel_hi:[1,0,1]
	v_pk_fma_f32 v[118:119], v[118:119], 0.5, v[122:123] op_sel_hi:[1,0,1]
	v_pk_fma_f32 v[122:123], v[116:117], 0.5, v[128:129] op_sel_hi:[1,0,1]
	v_pk_fma_f32 v[124:125], v[114:115], 0.5, v[126:127] op_sel_hi:[1,0,1]
	v_cvt_pk_bf16_f32 v114, v118, v119
	v_cvt_pk_bf16_f32 v115, v120, v121
	v_cvt_pk_bf16_f32 v116, v124, v125
	v_cvt_pk_bf16_f32 v117, v122, v123
	global_store_dwordx4 v[180:181], v[114:117], off offset:256
	s_nop 1
	v_mul_f32_e32 v114, v119, v119
	v_mul_f32_e32 v115, v121, v121
	v_fmac_f32_e32 v114, v118, v118
	v_fmac_f32_e32 v115, v120, v120
	v_add_f32_e32 v114, v114, v115
	v_mul_f32_e32 v115, v125, v125
	v_fmac_f32_e32 v115, v124, v124
	v_add_f32_e32 v114, v115, v114
	v_mul_f32_e32 v115, v123, v123
	v_fmac_f32_e32 v115, v122, v122
	v_add_f32_e32 v114, v115, v114
	v_add_f32_e32 v0, v0, v114
	v_mov_b32_e32 v114, v0
	s_nop 1
	v_permlane32_swap_b32_e32 v0, v114
	v_add_f32_e32 v0, v0, v114
	v_mov_b32_e32 v114, v0
	s_nop 1
	v_permlane16_swap_b32_e32 v0, v114
	s_and_saveexec_b64 s[62:63], vcc
	s_cbranch_execz .LBB0_612
	v_lshlrev_b64 v[116:117], 6, v[154:155]
	v_lshl_add_u64 v[116:117], s[12:13], 0, v[116:117]
	v_lshl_add_u64 v[116:117], s[58:59], 2, v[116:117]
	s_lshl_b32 s76, s45, 2
	s_mov_b32 s77, s19
	v_lshl_add_u64 v[116:117], v[116:117], 0, s[76:77]
	v_add_f32_e32 v0, v0, v114
	global_store_dword v[116:117], v0, off

; __device__ __forceinline__ u32x4 pack8(f32x4 a, f32x4 b) { u32x4 w; w.x = cvtpk(a[0], a[1]); w.y = cvtpk(a[2], a[3]); w.z = cvtpk(b[0], b[1]); w.w = cvtpk(b[2], b[3]); return w; }
;     __device__ __forceinline__ void operator()(AccRef acc, const Unit& u, int wr, int wc, int fr, int fq) const {
;     ...
;             for (int m = 0; m < 4; ++m) {
;                 const int row = u.pm * 256 + ai * 128 + wr * 64 + m * 16 + fr; float part = 0.f;
;                 const float sc = RS ? scale * rst[u.ui * 256 + ai * 128 + wr * 64 + m * 16 + fr] : scale;
; #pragma unroll
;                 for (int bj = 0; bj < 2; ++bj) {
;                     const size_t idx = (size_t)row * D + u.pn * 256 + bj * 128 + wc * 32 + 8 * fq;
;                     const u32x4 o4 = ow[m][bj];
;                     f32x4 v0, v1;
;                     v0[0] = __uint_as_float(o4.x << 16); v0[1] = __uint_as_float(o4.x & 0xffff0000u); v0[2] = __uint_as_float(o4.y << 16); v0[3] = __uint_as_float(o4.y & 0xffff0000u);
;                     v1[0] = __uint_as_float(o4.z << 16); v1[1] = __uint_as_float(o4.z & 0xffff0000u); v1[2] = __uint_as_float(o4.w << 16); v1[3] = __uint_as_float(o4.w & 0xffff0000u);
;                     v0 = v0 + acc[ai][bj][m][0] * sc; v1 = v1 + acc[ai][bj][m][1] * sc;
;                     *(u32x4*)(hb + idx) = pack8(v0, v1);
;                     part += (v0[0] * v0[0] + v0[1] * v0[1]) + (v0[2] * v0[2] + v0[3] * v0[3]) + (v1[0] * v1[0] + v1[1] * v1[1]) + (v1[2] * v1[2] + v1[3] * v1[3]);
;                 }
;                 part = fq_sum(part);
;                 if (fq == 0) ssn[(size_t)row * 16 + u.pn * 4 + wc] = part;
.LBB0_618:
	s_or_b64 exec, exec, s[62:63]
	v_add_u32_e32 v102, 0x80, v154
	v_ashrrev_i32_e32 v103, 31, v102
	v_add_u32_e32 v98, 0x90, v154
	v_lshlrev_b64 v[112:113], 11, v[102:103]
	v_ashrrev_i32_e32 v99, 31, v98
	v_add_u32_e32 v94, 0xa0, v154
	v_lshl_add_u64 v[66:67], v[156:157], 0, v[112:113]
	v_lshlrev_b64 v[100:101], 11, v[98:99]
	v_ashrrev_i32_e32 v95, 31, v94
	v_add_u32_e32 v90, 0xb0, v154
	v_lshl_add_u64 v[66:67], v[156:157], 0, v[100:101]
	v_lshlrev_b64 v[96:97], 11, v[94:95]
	v_ashrrev_i32_e32 v91, 31, v90
	v_lshl_add_u64 v[66:67], v[156:157], 0, v[96:97]
	v_lshlrev_b64 v[92:93], 11, v[90:91]
	v_lshl_add_u64 v[66:67], v[156:157], 0, v[92:93]
	s_nop 0
	v_lshl_add_u64 v[112:113], s[10:11], 0, v[112:113]
	s_waitcnt vmcnt(7)
	v_lshlrev_b32_e32 v114, 16, v196
	v_and_b32_e32 v115, 0xffff0000, v196
	v_lshlrev_b32_e32 v104, 16, v197
	v_and_b32_e32 v105, 0xffff0000, v197
	v_lshlrev_b32_e32 v116, 16, v198
	v_and_b32_e32 v117, 0xffff0000, v198
	v_lshlrev_b32_e32 v106, 16, v199
	v_and_b32_e32 v107, 0xffff0000, v199
	v_lshl_add_u64 v[112:113], s[60:61], 1, v[112:113]
	v_pk_fma_f32 v[64:65], v[64:65], 0.5, v[104:105] op_sel_hi:[1,0,1]
	v_pk_fma_f32 v[62:63], v[62:63], 0.5, v[114:115] op_sel_hi:[1,0,1]
	v_pk_fma_f32 v[104:105], v[60:61], 0.5, v[106:107] op_sel_hi:[1,0,1]
	v_pk_fma_f32 v[106:107], v[58:59], 0.5, v[116:117] op_sel_hi:[1,0,1]
	v_lshl_add_u64 v[112:113], v[112:113], 0, s[18:19]
	v_cvt_pk_bf16_f32 v58, v62, v63
	v_cvt_pk_bf16_f32 v59, v64, v65
	v_cvt_pk_bf16_f32 v60, v106, v107
	v_cvt_pk_bf16_f32 v61, v104, v105
	v_lshl_add_u64 v[112:113], v[112:113], 0, v[0:1]
	global_store_dwordx4 v[112:113], v[58:61], off
	s_nop 1
	v_mul_f32_e32 v58, v63, v63
	v_mul_f32_e32 v59, v65, v65
	v_fmac_f32_e32 v58, v62, v62
	v_fmac_f32_e32 v59, v64, v64
	v_add_f32_e32 v58, v58, v59
	v_mul_f32_e32 v59, v107, v107
	v_fmac_f32_e32 v59, v106, v106
	v_add_f32_e32 v58, v59, v58
	v_mul_f32_e32 v59, v105, v105
	v_fmac_f32_e32 v59, v104, v104
	v_add_f32_e32 v104, v59, v58
	s_waitcnt vmcnt(7)
	v_lshlrev_b32_e32 v58, 16, v200
	v_and_b32_e32 v59, 0xffff0000, v200
	v_lshlrev_b32_e32 v60, 16, v201
	v_and_b32_e32 v61, 0xffff0000, v201
	v_lshlrev_b32_e32 v62, 16, v202
	v_and_b32_e32 v63, 0xffff0000, v202
	v_lshlrev_b32_e32 v64, 16, v203
	v_and_b32_e32 v65, 0xffff0000, v203
	v_pk_fma_f32 v[56:57], v[56:57], 0.5, v[60:61] op_sel_hi:[1,0,1]
	v_pk_fma_f32 v[54:55], v[54:55], 0.5, v[58:59] op_sel_hi:[1,0,1]
	v_pk_fma_f32 v[58:59], v[52:53], 0.5, v[64:65] op_sel_hi:[1,0,1]
	v_pk_fma_f32 v[60:61], v[50:51], 0.5, v[62:63] op_sel_hi:[1,0,1]
	v_cvt_pk_bf16_f32 v50, v54, v55
	v_cvt_pk_bf16_f32 v51, v56, v57
	v_cvt_pk_bf16_f32 v52, v60, v61
	v_cvt_pk_bf16_f32 v53, v58, v59
	global_store_dwordx4 v[112:113], v[50:53], off offset:256
	s_nop 1
	v_mul_f32_e32 v50, v55, v55
	v_mul_f32_e32 v51, v57, v57
	v_fmac_f32_e32 v50, v54, v54
	v_fmac_f32_e32 v51, v56, v56
	v_add_f32_e32 v50, v50, v51
	v_mul_f32_e32 v51, v61, v61
	v_fmac_f32_e32 v51, v60, v60
	v_add_f32_e32 v50, v51, v50
	v_mul_f32_e32 v51, v59, v59
	v_fmac_f32_e32 v51, v58, v58
	v_add_f32_e32 v50, v51, v50
	v_add_f32_e32 v50, v104, v50
	v_mov_b32_e32 v51, v50
	s_nop 1
	v_permlane32_swap_b32_e32 v50, v51
	v_add_f32_e32 v50, v50, v51
	v_mov_b32_e32 v51, v50
	s_nop 1
	v_permlane16_swap_b32_e32 v50, v51
	s_and_saveexec_b64 s[62:63], vcc
	s_cbranch_execz .LBB0_620
	v_lshlrev_b64 v[52:53], 6, v[102:103]
	v_lshl_add_u64 v[52:53], s[12:13], 0, v[52:53]
	v_lshl_add_u64 v[52:53], s[58:59], 2, v[52:53]
	s_lshl_b32 s76, s45, 2
	s_mov_b32 s77, s19
	v_lshl_add_u64 v[52:53], v[52:53], 0, s[76:77]
	v_add_f32_e32 v50, v50, v51
	global_store_dword v[52:53], v50, off
.LBB0_620:
	s_or_b64 exec, exec, s[62:63]
	s_waitcnt vmcnt(7)
	v_lshlrev_b32_e32 v52, 16, v207
	v_and_b32_e32 v53, 0xffff0000, v207
	v_lshlrev_b32_e32 v54, 16, v208
	v_and_b32_e32 v55, 0xffff0000, v208
	v_pk_fma_f32 v[48:49], v[48:49], 0.5, v[52:53] op_sel_hi:[1,0,1]
	v_pk_fma_f32 v[52:53], v[42:43], 0.5, v[54:55] op_sel_hi:[1,0,1]
	v_lshl_add_u64 v[54:55], s[10:11], 0, v[100:101]
	v_lshlrev_b32_e32 v50, 16, v206
	v_and_b32_e32 v51, 0xffff0000, v206
	v_lshlrev_b32_e32 v56, 16, v209
	v_and_b32_e32 v57, 0xffff0000, v209
	v_lshl_add_u64 v[54:55], s[60:61], 1, v[54:55]
	v_pk_fma_f32 v[46:47], v[46:47], 0.5, v[50:51] op_sel_hi:[1,0,1]
	v_pk_fma_f32 v[50:51], v[44:45], 0.5, v[56:57] op_sel_hi:[1,0,1]
	v_lshl_add_u64 v[54:55], v[54:55], 0, s[18:19]
	v_cvt_pk_bf16_f32 v42, v46, v47
	v_cvt_pk_bf16_f32 v43, v48, v49
	v_cvt_pk_bf16_f32 v44, v52, v53
	v_cvt_pk_bf16_f32 v45, v50, v51
	v_lshl_add_u64 v[54:55], v[54:55], 0, v[0:1]
	global_store_dwordx4 v[54:55], v[42:45], off
	s_nop 1
	v_mul_f32_e32 v42, v47, v47
	v_mul_f32_e32 v43, v49, v49
	v_fmac_f32_e32 v42, v46, v46
	v_fmac_f32_e32 v43, v48, v48
	v_add_f32_e32 v42, v42, v43
	v_mul_f32_e32 v43, v53, v53
	v_fmac_f32_e32 v43, v52, v52
	v_add_f32_e32 v42, v43, v42
	v_mul_f32_e32 v43, v51, v51
	v_fmac_f32_e32 v43, v50, v50
	v_add_f32_e32 v50, v43, v42
	s_waitcnt vmcnt(7)
	v_lshlrev_b32_e32 v42, 16, v210
	v_and_b32_e32 v43, 0xffff0000, v210
	v_lshlrev_b32_e32 v44, 16, v211
	v_and_b32_e32 v45, 0xffff0000, v211
	v_lshlrev_b32_e32 v46, 16, v212
	v_and_b32_e32 v47, 0xffff0000, v212
	v_lshlrev_b32_e32 v48, 16, v213
	v_and_b32_e32 v49, 0xffff0000, v213
	v_pk_fma_f32 v[40:41], v[40:41], 0.5, v[44:45] op_sel_hi:[1,0,1]
	v_pk_fma_f32 v[38:39], v[38:39], 0.5, v[42:43] op_sel_hi:[1,0,1]
	v_pk_fma_f32 v[42:43], v[36:37], 0.5, v[48:49] op_sel_hi:[1,0,1]
	v_pk_fma_f32 v[44:45], v[34:35], 0.5, v[46:47] op_sel_hi:[1,0,1]
	v_cvt_pk_bf16_f32 v34, v38, v39
	v_cvt_pk_bf16_f32 v35, v40, v41
	v_cvt_pk_bf16_f32 v36, v44, v45
	v_cvt_pk_bf16_f32 v37, v42, v43
	global_store_dwordx4 v[54:55], v[34:37], off offset:256
	s_nop 1
	v_mul_f32_e32 v34, v39, v39
	v_mul_f32_e32 v35, v41, v41
	v_fmac_f32_e32 v34, v38, v38
	v_fmac_f32_e32 v35, v40, v40
	v_add_f32_e32 v34, v34, v35
	v_mul_f32_e32 v35, v45, v45
	v_fmac_f32_e32 v35, v44, v44
	v_add_f32_e32 v34, v35, v34
	v_mul_f32_e32 v35, v43, v43
	v_fmac_f32_e32 v35, v42, v42
	v_add_f32_e32 v34, v35, v34
	v_add_f32_e32 v34, v50, v34
	v_mov_b32_e32 v35, v34
	s_nop 1
	v_permlane32_swap_b32_e32 v34, v35
	v_add_f32_e32 v34, v34, v35
	v_mov_b32_e32 v35, v34
	s_nop 1
	v_permlane16_swap_b32_e32 v34, v35
	s_and_saveexec_b64 s[62:63], vcc
	s_cbranch_execz .LBB0_622
	v_lshlrev_b64 v[36:37], 6, v[98:99]
	v_lshl_add_u64 v[36:37], s[12:13], 0, v[36:37]
	v_lshl_add_u64 v[36:37], s[58:59], 2, v[36:37]
	s_lshl_b32 s76, s45, 2
	s_mov_b32 s77, s19
	v_lshl_add_u64 v[36:37], v[36:37], 0, s[76:77]
	v_add_f32_e32 v34, v34, v35
	global_store_dword v[36:37], v34, off
; __device__ __forceinline__ u32x4 pack8(f32x4 a, f32x4 b) { u32x4 w; w.x = cvtpk(a[0], a[1]); w.y = cvtpk(a[2], a[3]); w.z = cvtpk(b[0], b[1]); w.w = cvtpk(b[2], b[3]); return w; }
;     __device__ __forceinline__ void operator()(AccRef acc, const Unit& u, int wr, int wc, int fr, int fq) const {
;     ...
;             for (int m = 0; m < 4; ++m) {
;                 const int row = u.pm * 256 + ai * 128 + wr * 64 + m * 16 + fr; float part = 0.f;
;                 const float sc = RS ? scale * rst[u.ui * 256 + ai * 128 + wr * 64 + m * 16 + fr] : scale;
; #pragma unroll
;                 for (int bj = 0; bj < 2; ++bj) {
;                     const size_t idx = (size_t)row * D + u.pn * 256 + bj * 128 + wc * 32 + 8 * fq;
;                     const u32x4 o4 = ow[m][bj];
;                     f32x4 v0, v1;
;                     v0[0] = __uint_as_float(o4.x << 16); v0[1] = __uint_as_float(o4.x & 0xffff0000u); v0[2] = __uint_as_float(o4.y << 16); v0[3] = __uint_as_float(o4.y & 0xffff0000u);
;                     v1[0] = __uint_as_float(o4.z << 16); v1[1] = __uint_as_float(o4.z & 0xffff0000u); v1[2] = __uint_as_float(o4.w << 16); v1[3] = __uint_as_float(o4.w & 0xffff0000u);
;                     v0 = v0 + acc[ai][bj][m][0] * sc; v1 = v1 + acc[ai][bj][m][1] * sc;
;                     *(u32x4*)(hb + idx) = pack8(v0, v1);
;                     part += (v0[0] * v0[0] + v0[1] * v0[1]) + (v0[2] * v0[2] + v0[3] * v0[3]) + (v1[0] * v1[0] + v1[1] * v1[1]) + (v1[2] * v1[2] + v1[3] * v1[3]);
;                 }
;                 part = fq_sum(part);
;                 if (fq == 0) ssn[(size_t)row * 16 + u.pn * 4 + wc] = part;
.LBB0_622:
	s_or_b64 exec, exec, s[62:63]
	s_waitcnt vmcnt(7)
	v_lshlrev_b32_e32 v36, 16, v239
	v_and_b32_e32 v37, 0xffff0000, v239
	v_lshlrev_b32_e32 v38, 16, v240
	v_and_b32_e32 v39, 0xffff0000, v240
	v_pk_fma_f32 v[32:33], v[32:33], 0.5, v[36:37] op_sel_hi:[1,0,1]
	v_pk_fma_f32 v[36:37], v[26:27], 0.5, v[38:39] op_sel_hi:[1,0,1]
	v_lshl_add_u64 v[38:39], s[10:11], 0, v[96:97]
	v_lshlrev_b32_e32 v34, 16, v238
	v_and_b32_e32 v35, 0xffff0000, v238
	v_lshlrev_b32_e32 v40, 16, v241
	v_and_b32_e32 v41, 0xffff0000, v241
	v_lshl_add_u64 v[38:39], s[60:61], 1, v[38:39]
	v_pk_fma_f32 v[30:31], v[30:31], 0.5, v[34:35] op_sel_hi:[1,0,1]
	v_pk_fma_f32 v[34:35], v[28:29], 0.5, v[40:41] op_sel_hi:[1,0,1]
	v_lshl_add_u64 v[38:39], v[38:39], 0, s[18:19]
	v_cvt_pk_bf16_f32 v26, v30, v31
	v_cvt_pk_bf16_f32 v27, v32, v33
	v_cvt_pk_bf16_f32 v28, v36, v37
	v_cvt_pk_bf16_f32 v29, v34, v35
	v_lshl_add_u64 v[38:39], v[38:39], 0, v[0:1]
	global_store_dwordx4 v[38:39], v[26:29], off
	s_nop 1
	v_mul_f32_e32 v26, v31, v31
	v_mul_f32_e32 v27, v33, v33
	v_fmac_f32_e32 v26, v30, v30
	v_fmac_f32_e32 v27, v32, v32
	v_add_f32_e32 v26, v26, v27
	v_mul_f32_e32 v27, v37, v37
	v_fmac_f32_e32 v27, v36, v36
	v_add_f32_e32 v26, v27, v26
	v_mul_f32_e32 v27, v35, v35
	v_fmac_f32_e32 v27, v34, v34
	v_add_f32_e32 v34, v27, v26
	s_waitcnt vmcnt(7)
	v_lshlrev_b32_e32 v26, 16, v242
	v_and_b32_e32 v27, 0xffff0000, v242
	v_lshlrev_b32_e32 v28, 16, v243
	v_and_b32_e32 v29, 0xffff0000, v243
	v_lshlrev_b32_e32 v30, 16, v244
	v_and_b32_e32 v31, 0xffff0000, v244
	v_lshlrev_b32_e32 v32, 16, v245
	v_and_b32_e32 v33, 0xffff0000, v245
	v_pk_fma_f32 v[24:25], v[24:25], 0.5, v[28:29] op_sel_hi:[1,0,1]
	v_pk_fma_f32 v[22:23], v[22:23], 0.5, v[26:27] op_sel_hi:[1,0,1]
	v_pk_fma_f32 v[26:27], v[20:21], 0.5, v[32:33] op_sel_hi:[1,0,1]
	v_pk_fma_f32 v[28:29], v[18:19], 0.5, v[30:31] op_sel_hi:[1,0,1]
	v_cvt_pk_bf16_f32 v18, v22, v23
	v_cvt_pk_bf16_f32 v19, v24, v25
	v_cvt_pk_bf16_f32 v20, v28, v29
	v_cvt_pk_bf16_f32 v21, v26, v27
	global_store_dwordx4 v[38:39], v[18:21], off offset:256
	s_nop 1
	v_mul_f32_e32 v18, v23, v23
	v_mul_f32_e32 v19, v25, v25
	v_fmac_f32_e32 v18, v22, v22
	v_fmac_f32_e32 v19, v24, v24
	v_add_f32_e32 v18, v18, v19
	v_mul_f32_e32 v19, v29, v29
	v_fmac_f32_e32 v19, v28, v28
	v_add_f32_e32 v18, v19, v18
	v_mul_f32_e32 v19, v27, v27
	v_fmac_f32_e32 v19, v26, v26
	v_add_f32_e32 v18, v19, v18
	v_add_f32_e32 v18, v34, v18
	v_mov_b32_e32 v19, v18
	s_nop 1
	v_permlane32_swap_b32_e32 v18, v19
	v_add_f32_e32 v18, v18, v19
	v_mov_b32_e32 v19, v18
	s_nop 1
	v_permlane16_swap_b32_e32 v18, v19
	s_and_saveexec_b64 s[62:63], vcc
	s_cbranch_execz .LBB0_624
	v_lshlrev_b64 v[20:21], 6, v[94:95]
	v_lshl_add_u64 v[20:21], s[12:13], 0, v[20:21]
	v_lshl_add_u64 v[20:21], s[58:59], 2, v[20:21]
	s_lshl_b32 s76, s45, 2
	s_mov_b32 s77, s19
	v_lshl_add_u64 v[20:21], v[20:21], 0, s[76:77]
	v_add_f32_e32 v18, v18, v19
	global_store_dword v[20:21], v18, off
.LBB0_624:
	s_or_b64 exec, exec, s[62:63]
	s_waitcnt vmcnt(7)
	v_lshlrev_b32_e32 v20, 16, v247
	v_and_b32_e32 v21, 0xffff0000, v247
	v_lshlrev_b32_e32 v22, 16, v248
	v_and_b32_e32 v23, 0xffff0000, v248
	v_pk_fma_f32 v[16:17], v[16:17], 0.5, v[20:21] op_sel_hi:[1,0,1]
	v_pk_fma_f32 v[20:21], v[10:11], 0.5, v[22:23] op_sel_hi:[1,0,1]
	v_lshl_add_u64 v[22:23], s[10:11], 0, v[92:93]
	v_lshlrev_b32_e32 v18, 16, v246
	v_and_b32_e32 v19, 0xffff0000, v246
	v_lshlrev_b32_e32 v24, 16, v249
	v_and_b32_e32 v25, 0xffff0000, v249
	v_lshl_add_u64 v[22:23], s[60:61], 1, v[22:23]
	v_pk_fma_f32 v[14:15], v[14:15], 0.5, v[18:19] op_sel_hi:[1,0,1]
	v_pk_fma_f32 v[18:19], v[12:13], 0.5, v[24:25] op_sel_hi:[1,0,1]
	v_lshl_add_u64 v[22:23], v[22:23], 0, s[18:19]
	v_cvt_pk_bf16_f32 v10, v14, v15
	v_cvt_pk_bf16_f32 v11, v16, v17
	v_cvt_pk_bf16_f32 v12, v20, v21
	v_cvt_pk_bf16_f32 v13, v18, v19
	v_lshl_add_u64 v[22:23], v[22:23], 0, v[0:1]
	global_store_dwordx4 v[22:23], v[10:13], off
	v_mul_f32_e32 v0, v15, v15
	v_fmac_f32_e32 v0, v14, v14
	v_mul_f32_e32 v10, v17, v17
	v_fmac_f32_e32 v10, v16, v16
	v_add_f32_e32 v0, v0, v10
	v_mul_f32_e32 v10, v21, v21
	v_fmac_f32_e32 v10, v20, v20
	v_add_f32_e32 v0, v10, v0
	v_mul_f32_e32 v10, v19, v19
	v_fmac_f32_e32 v10, v18, v18
	v_add_f32_e32 v0, v10, v0
	s_waitcnt vmcnt(7)
	v_lshlrev_b32_e32 v10, 16, v250
	v_and_b32_e32 v11, 0xffff0000, v250
	v_lshlrev_b32_e32 v12, 16, v251
	v_and_b32_e32 v13, 0xffff0000, v251
	v_lshlrev_b32_e32 v14, 16, v252
	v_and_b32_e32 v15, 0xffff0000, v252
	v_lshlrev_b32_e32 v16, 16, v253
	v_and_b32_e32 v17, 0xffff0000, v253
	v_pk_fma_f32 v[8:9], v[8:9], 0.5, v[12:13] op_sel_hi:[1,0,1]
	v_pk_fma_f32 v[6:7], v[6:7], 0.5, v[10:11] op_sel_hi:[1,0,1]
	v_pk_fma_f32 v[10:11], v[4:5], 0.5, v[16:17] op_sel_hi:[1,0,1]
	v_pk_fma_f32 v[12:13], v[2:3], 0.5, v[14:15] op_sel_hi:[1,0,1]
	v_cvt_pk_bf16_f32 v2, v6, v7
	v_cvt_pk_bf16_f32 v3, v8, v9
	v_cvt_pk_bf16_f32 v4, v12, v13
	v_cvt_pk_bf16_f32 v5, v10, v11
	global_store_dwordx4 v[22:23], v[2:5], off offset:256
	s_nop 1
	v_mul_f32_e32 v2, v7, v7
	v_mul_f32_e32 v3, v9, v9
	v_fmac_f32_e32 v2, v6, v6
	v_fmac_f32_e32 v3, v8, v8
	v_add_f32_e32 v2, v2, v3
	v_mul_f32_e32 v3, v13, v13
	v_fmac_f32_e32 v3, v12, v12
	v_add_f32_e32 v2, v3, v2
	v_mul_f32_e32 v3, v11, v11
	v_fmac_f32_e32 v3, v10, v10
	v_add_f32_e32 v2, v3, v2
	v_add_f32_e32 v0, v0, v2
	v_mov_b32_e32 v2, v0
	s_nop 1
	v_permlane32_swap_b32_e32 v0, v2
	v_add_f32_e32 v0, v0, v2
	v_mov_b32_e32 v2, v0
	s_nop 1
	v_permlane16_swap_b32_e32 v0, v2
	s_and_saveexec_b64 s[60:61], vcc
	s_cbranch_execz .LBB0_626
	v_lshlrev_b64 v[4:5], 6, v[90:91]
	v_lshl_add_u64 v[4:5], s[12:13], 0, v[4:5]
	v_lshl_add_u64 v[4:5], s[58:59], 2, v[4:5]
	s_lshl_b32 s18, s45, 2
	v_lshl_add_u64 v[4:5], v[4:5], 0, s[18:19]
	v_add_f32_e32 v0, v0, v2
	global_store_dword v[4:5], v0, off

; __device__ __forceinline__ u32x4 pack8(f32x4 a, f32x4 b) { u32x4 w; w.x = cvtpk(a[0], a[1]); w.y = cvtpk(a[2], a[3]); w.z = cvtpk(b[0], b[1]); w.w = cvtpk(b[2], b[3]); return w; }
;     __device__ __forceinline__ void operator()(AccRef acc, const Unit& u, int wr, int wc, int fr, int fq) const {
; #pragma unroll
;         for (int ai = 0; ai < 2; ++ai) {
;             u32x4 ow[4][2];
; #pragma unroll
;             for (int m = 0; m < 4; ++m)
; #pragma unroll
;                 for (int bj = 0; bj < 2; ++bj)
;                     ow[m][bj] = *(const u32x4*)(hb + (size_t)(u.pm * 256 + ai * 128 + wr * 64 + m * 16 + fr) * D + u.pn * 256 + bj * 128 + wc * 32 + 8 * fq);
;             __builtin_amdgcn_sched_barrier(0);
; #pragma unroll
;             for (int m = 0; m < 4; ++m) {
;                 const int row = u.pm * 256 + ai * 128 + wr * 64 + m * 16 + fr; float part = 0.f;
;                 const float sc = RS ? scale * rst[u.ui * 256 + ai * 128 + wr * 64 + m * 16 + fr] : scale;
; #pragma unroll
;                 for (int bj = 0; bj < 2; ++bj) {
;                     const size_t idx = (size_t)row * D + u.pn * 256 + bj * 128 + wc * 32 + 8 * fq;
;                     const u32x4 o4 = ow[m][bj];
;                     f32x4 v0, v1;
;                     v0[0] = __uint_as_float(o4.x << 16); v0[1] = __uint_as_float(o4.x & 0xffff0000u); v0[2] = __uint_as_float(o4.y << 16); v0[3] = __uint_as_float(o4.y & 0xffff0000u);
;                     v1[0] = __uint_as_float(o4.z << 16); v1[1] = __uint_as_float(o4.z & 0xffff0000u); v1[2] = __uint_as_float(o4.w << 16); v1[3] = __uint_as_float(o4.w & 0xffff0000u);
;                     v0 = v0 + acc[ai][bj][m][0] * sc; v1 = v1 + acc[ai][bj][m][1] * sc;
;                     *(u32x4*)(hb + idx) = pack8(v0, v1);
;                     part += (v0[0] * v0[0] + v0[1] * v0[1]) + (v0[2] * v0[2] + v0[3] * v0[3]) + (v1[0] * v1[0] + v1[1] * v1[1]) + (v1[2] * v1[2] + v1[3] * v1[3]);
;                 }
;                 part = fq_sum(part);
;                 if (fq == 0) ssn[(size_t)row * 16 + u.pn * 4 + wc] = part;
.LBB0_1895:
	s_lshl_b32 s56, s72, 8
	s_lshl_b32 s17, s73, 8
	s_ashr_i32 s57, s56, 31
	s_lshl_b32 s54, s72, 2
	v_mov_b32_e32 v0, v236
	s_add_i32 s17, s17, s46
	s_ashr_i32 s55, s54, 31
	s_lshl_b64 s[58:59], s[56:57], 1
	s_add_u32 s72, s67, s58
	v_bfe_u32 v170, v0, 4, 2
	v_and_or_b32 v154, v0, 15, s17
	s_addc_u32 s73, s68, s59
	v_lshlrev_b32_e32 v0, 4, v170
	v_ashrrev_i32_e32 v155, 31, v154
	v_or_b32_e32 v166, 16, v154
	v_lshl_add_u64 v[156:157], s[72:73], 0, v[0:1]
	v_lshlrev_b64 v[180:181], 11, v[154:155]
	v_ashrrev_i32_e32 v167, 31, v166
	v_or_b32_e32 v162, 32, v154
	v_lshl_add_u64 v[130:131], v[156:157], 0, v[180:181]
	v_lshlrev_b64 v[168:169], 11, v[166:167]
	v_ashrrev_i32_e32 v163, 31, v162
	v_or_b32_e32 v158, 48, v154
	global_load_dwordx4 v[172:175], v[130:131], off
	global_load_dwordx4 v[176:179], v[130:131], off offset:256
	v_lshl_add_u64 v[130:131], v[156:157], 0, v[168:169]
	v_lshlrev_b64 v[164:165], 11, v[162:163]
	v_ashrrev_i32_e32 v159, 31, v158
	global_load_dwordx4 v[150:153], v[130:131], off
	global_load_dwordx4 v[146:149], v[130:131], off offset:256
	v_lshl_add_u64 v[130:131], v[156:157], 0, v[164:165]
	v_lshlrev_b64 v[160:161], 11, v[158:159]
	global_load_dwordx4 v[142:145], v[130:131], off
	global_load_dwordx4 v[138:141], v[130:131], off offset:256
	v_lshl_add_u64 v[130:131], v[156:157], 0, v[160:161]
	global_load_dwordx4 v[134:137], v[130:131], off
	s_nop 0
	global_load_dwordx4 v[130:133], v[130:131], off offset:256
	v_mov_b32_e32 v190, 0x40000
	v_mov_b32_e32 v191, 0
	v_lshl_add_u64 v[216:217], v[190:191], 0, v[180:181]
	v_lshl_add_u64 v[216:217], v[156:157], 0, v[216:217]
	global_load_dwordx4 v[186:189], v[216:217], off
	global_load_dwordx4 v[196:199], v[216:217], off offset:256
	v_lshl_add_u64 v[216:217], v[190:191], 0, v[168:169]
	v_lshl_add_u64 v[216:217], v[156:157], 0, v[216:217]
	global_load_dwordx4 v[200:203], v[216:217], off
	global_load_dwordx4 v[204:207], v[216:217], off offset:256
	v_lshl_add_u64 v[216:217], v[190:191], 0, v[164:165]
	v_lshl_add_u64 v[216:217], v[156:157], 0, v[216:217]
	global_load_dwordx4 v[208:211], v[216:217], off
	global_load_dwordx4 v[212:215], v[216:217], off offset:256
	v_lshl_add_u64 v[216:217], v[190:191], 0, v[160:161]
	v_lshl_add_u64 v[216:217], v[156:157], 0, v[216:217]
	global_load_dwordx4 v[220:223], v[216:217], off
	global_load_dwordx4 v[238:241], v[216:217], off offset:256
	v_cmp_eq_u32_e32 vcc, 0, v170
	v_lshl_add_u64 v[180:181], s[10:11], 0, v[180:181]
	s_waitcnt vmcnt(0)
	v_lshlrev_b32_e32 v182, 16, v172
	v_and_b32_e32 v183, 0xffff0000, v172
	v_lshlrev_b32_e32 v172, 16, v173
	v_and_b32_e32 v173, 0xffff0000, v173
	v_lshlrev_b32_e32 v184, 16, v174
	v_and_b32_e32 v185, 0xffff0000, v174
	v_lshlrev_b32_e32 v174, 16, v175
	v_and_b32_e32 v175, 0xffff0000, v175
	v_lshl_add_u64 v[180:181], v[180:181], 0, s[58:59]
	s_lshl_b32 s18, s60, 1
	v_pk_add_f32 v[128:129], v[128:129], v[172:173]
	v_pk_add_f32 v[126:127], v[126:127], v[182:183]
	v_pk_add_f32 v[172:173], v[124:125], v[174:175]
	v_pk_add_f32 v[174:175], v[122:123], v[184:185]
	v_lshl_add_u64 v[180:181], v[180:181], 0, s[18:19]
	v_cvt_pk_bf16_f32 v122, v126, v127
	v_cvt_pk_bf16_f32 v123, v128, v129
	v_cvt_pk_bf16_f32 v124, v174, v175
	v_cvt_pk_bf16_f32 v125, v172, v173
	v_lshl_add_u64 v[180:181], v[180:181], 0, v[0:1]
	global_store_dwordx4 v[180:181], v[122:125], off
	v_mul_f32_e32 v0, v127, v127
	v_fmac_f32_e32 v0, v126, v126
	v_mul_f32_e32 v122, v129, v129
	v_fmac_f32_e32 v122, v128, v128
	v_add_f32_e32 v0, v0, v122
	v_mul_f32_e32 v122, v175, v175
	v_fmac_f32_e32 v122, v174, v174
	v_add_f32_e32 v0, v122, v0
	v_mul_f32_e32 v122, v173, v173
	v_fmac_f32_e32 v122, v172, v172
	v_add_f32_e32 v0, v122, v0
	v_lshlrev_b32_e32 v122, 16, v176
	v_and_b32_e32 v123, 0xffff0000, v176
	v_lshlrev_b32_e32 v124, 16, v177
	v_and_b32_e32 v125, 0xffff0000, v177
	v_lshlrev_b32_e32 v126, 16, v178
	v_and_b32_e32 v127, 0xffff0000, v178
	v_lshlrev_b32_e32 v128, 16, v179
	v_and_b32_e32 v129, 0xffff0000, v179
	v_pk_add_f32 v[120:121], v[120:121], v[124:125]
	v_pk_add_f32 v[118:119], v[118:119], v[122:123]
	v_pk_add_f32 v[122:123], v[116:117], v[128:129]
	v_pk_add_f32 v[124:125], v[114:115], v[126:127]
	v_cvt_pk_bf16_f32 v114, v118, v119
	v_cvt_pk_bf16_f32 v115, v120, v121
	v_cvt_pk_bf16_f32 v116, v124, v125
	v_cvt_pk_bf16_f32 v117, v122, v123
	global_store_dwordx4 v[180:181], v[114:117], off offset:256
	s_nop 1
	v_mul_f32_e32 v114, v119, v119
	v_mul_f32_e32 v115, v121, v121
	v_fmac_f32_e32 v114, v118, v118
	v_fmac_f32_e32 v115, v120, v120
	v_add_f32_e32 v114, v114, v115
	v_mul_f32_e32 v115, v125, v125
	v_fmac_f32_e32 v115, v124, v124
	v_add_f32_e32 v114, v115, v114
	v_mul_f32_e32 v115, v123, v123
	v_fmac_f32_e32 v115, v122, v122
	v_add_f32_e32 v114, v115, v114
	v_add_f32_e32 v0, v0, v114
	v_mov_b32_e32 v114, v0
	s_nop 1
	v_permlane32_swap_b32_e32 v0, v114
	v_add_f32_e32 v0, v0, v114
	v_mov_b32_e32 v114, v0
	s_nop 1
	v_permlane16_swap_b32_e32 v0, v114
	s_and_saveexec_b64 s[58:59], vcc
	s_cbranch_execz .LBB0_1897
	v_lshlrev_b64 v[116:117], 6, v[154:155]
	v_lshl_add_u64 v[116:117], s[12:13], 0, v[116:117]
	v_lshl_add_u64 v[116:117], s[54:55], 2, v[116:117]
	s_lshl_b32 s72, s45, 2
	s_mov_b32 s73, s19
	v_lshl_add_u64 v[116:117], v[116:117], 0, s[72:73]
	v_add_f32_e32 v0, v0, v114
	global_store_dword v[116:117], v0, off

; __device__ __forceinline__ u32x4 pack8(f32x4 a, f32x4 b) { u32x4 w; w.x = cvtpk(a[0], a[1]); w.y = cvtpk(a[2], a[3]); w.z = cvtpk(b[0], b[1]); w.w = cvtpk(b[2], b[3]); return w; }
;     __device__ __forceinline__ void operator()(AccRef acc, const Unit& u, int wr, int wc, int fr, int fq) const {
;     ...
;             for (int m = 0; m < 4; ++m) {
;                 const int row = u.pm * 256 + ai * 128 + wr * 64 + m * 16 + fr; float part = 0.f;
;                 const float sc = RS ? scale * rst[u.ui * 256 + ai * 128 + wr * 64 + m * 16 + fr] : scale;
; #pragma unroll
;                 for (int bj = 0; bj < 2; ++bj) {
;                     const size_t idx = (size_t)row * D + u.pn * 256 + bj * 128 + wc * 32 + 8 * fq;
;                     const u32x4 o4 = ow[m][bj];
;                     f32x4 v0, v1;
;                     v0[0] = __uint_as_float(o4.x << 16); v0[1] = __uint_as_float(o4.x & 0xffff0000u); v0[2] = __uint_as_float(o4.y << 16); v0[3] = __uint_as_float(o4.y & 0xffff0000u);
;                     v1[0] = __uint_as_float(o4.z << 16); v1[1] = __uint_as_float(o4.z & 0xffff0000u); v1[2] = __uint_as_float(o4.w << 16); v1[3] = __uint_as_float(o4.w & 0xffff0000u);
;                     v0 = v0 + acc[ai][bj][m][0] * sc; v1 = v1 + acc[ai][bj][m][1] * sc;
;                     *(u32x4*)(hb + idx) = pack8(v0, v1);
;                     part += (v0[0] * v0[0] + v0[1] * v0[1]) + (v0[2] * v0[2] + v0[3] * v0[3]) + (v1[0] * v1[0] + v1[1] * v1[1]) + (v1[2] * v1[2] + v1[3] * v1[3]);
;                 }
;                 part = fq_sum(part);
;                 if (fq == 0) ssn[(size_t)row * 16 + u.pn * 4 + wc] = part;
.LBB0_1903:
	s_or_b64 exec, exec, s[58:59]
	v_add_u32_e32 v102, 0x80, v154
	v_ashrrev_i32_e32 v103, 31, v102
	v_add_u32_e32 v98, 0x90, v154
	v_lshlrev_b64 v[112:113], 11, v[102:103]
	v_ashrrev_i32_e32 v99, 31, v98
	v_add_u32_e32 v94, 0xa0, v154
	v_lshl_add_u64 v[66:67], v[156:157], 0, v[112:113]
	v_lshlrev_b64 v[100:101], 11, v[98:99]
	v_ashrrev_i32_e32 v95, 31, v94
	v_add_u32_e32 v90, 0xb0, v154
	v_lshl_add_u64 v[66:67], v[156:157], 0, v[100:101]
	v_lshlrev_b64 v[96:97], 11, v[94:95]
	v_ashrrev_i32_e32 v91, 31, v90
	v_lshl_add_u64 v[66:67], v[156:157], 0, v[96:97]
	v_lshlrev_b64 v[92:93], 11, v[90:91]
	v_lshl_add_u64 v[66:67], v[156:157], 0, v[92:93]
	s_nop 0
	v_lshl_add_u64 v[112:113], s[10:11], 0, v[112:113]
	s_waitcnt vmcnt(7)
	v_lshlrev_b32_e32 v114, 16, v186
	v_and_b32_e32 v115, 0xffff0000, v186
	v_lshlrev_b32_e32 v104, 16, v187
	v_and_b32_e32 v105, 0xffff0000, v187
	v_lshlrev_b32_e32 v116, 16, v188
	v_and_b32_e32 v117, 0xffff0000, v188
	v_lshlrev_b32_e32 v106, 16, v189
	v_and_b32_e32 v107, 0xffff0000, v189
	v_lshl_add_u64 v[112:113], s[56:57], 1, v[112:113]
	v_pk_add_f32 v[64:65], v[64:65], v[104:105]
	v_pk_add_f32 v[62:63], v[62:63], v[114:115]
	v_pk_add_f32 v[104:105], v[60:61], v[106:107]
	v_pk_add_f32 v[106:107], v[58:59], v[116:117]
	v_lshl_add_u64 v[112:113], v[112:113], 0, s[18:19]
	v_cvt_pk_bf16_f32 v58, v62, v63
	v_cvt_pk_bf16_f32 v59, v64, v65
	v_cvt_pk_bf16_f32 v60, v106, v107
	v_cvt_pk_bf16_f32 v61, v104, v105
	v_lshl_add_u64 v[112:113], v[112:113], 0, v[0:1]
	global_store_dwordx4 v[112:113], v[58:61], off
	s_nop 1
	v_mul_f32_e32 v58, v63, v63
	v_mul_f32_e32 v59, v65, v65
	v_fmac_f32_e32 v58, v62, v62
	v_fmac_f32_e32 v59, v64, v64
	v_add_f32_e32 v58, v58, v59
	v_mul_f32_e32 v59, v107, v107
	v_fmac_f32_e32 v59, v106, v106
	v_add_f32_e32 v58, v59, v58
	v_mul_f32_e32 v59, v105, v105
	v_fmac_f32_e32 v59, v104, v104
	v_add_f32_e32 v104, v59, v58
	s_waitcnt vmcnt(7)
	v_lshlrev_b32_e32 v58, 16, v196
	v_and_b32_e32 v59, 0xffff0000, v196
	v_lshlrev_b32_e32 v60, 16, v197
	v_and_b32_e32 v61, 0xffff0000, v197
	v_lshlrev_b32_e32 v62, 16, v198
	v_and_b32_e32 v63, 0xffff0000, v198
	v_lshlrev_b32_e32 v64, 16, v199
	v_and_b32_e32 v65, 0xffff0000, v199
	v_pk_add_f32 v[56:57], v[56:57], v[60:61]
	v_pk_add_f32 v[54:55], v[54:55], v[58:59]
	v_pk_add_f32 v[58:59], v[52:53], v[64:65]
	v_pk_add_f32 v[60:61], v[50:51], v[62:63]
	v_cvt_pk_bf16_f32 v50, v54, v55
	v_cvt_pk_bf16_f32 v51, v56, v57
	v_cvt_pk_bf16_f32 v52, v60, v61
	v_cvt_pk_bf16_f32 v53, v58, v59
	global_store_dwordx4 v[112:113], v[50:53], off offset:256
	s_nop 1
	v_mul_f32_e32 v50, v55, v55
	v_mul_f32_e32 v51, v57, v57
	v_fmac_f32_e32 v50, v54, v54
	v_fmac_f32_e32 v51, v56, v56
	v_add_f32_e32 v50, v50, v51
	v_mul_f32_e32 v51, v61, v61
	v_fmac_f32_e32 v51, v60, v60
	v_add_f32_e32 v50, v51, v50
	v_mul_f32_e32 v51, v59, v59
	v_fmac_f32_e32 v51, v58, v58
	v_add_f32_e32 v50, v51, v50
	v_add_f32_e32 v50, v104, v50
	v_mov_b32_e32 v51, v50
	s_nop 1
	v_permlane32_swap_b32_e32 v50, v51
	v_add_f32_e32 v50, v50, v51
	v_mov_b32_e32 v51, v50
	s_nop 1
	v_permlane16_swap_b32_e32 v50, v51
	s_and_saveexec_b64 s[58:59], vcc
	s_cbranch_execz .LBB0_1905
	v_lshlrev_b64 v[52:53], 6, v[102:103]
	v_lshl_add_u64 v[52:53], s[12:13], 0, v[52:53]
	v_lshl_add_u64 v[52:53], s[54:55], 2, v[52:53]
	s_lshl_b32 s72, s45, 2
	s_mov_b32 s73, s19
	v_lshl_add_u64 v[52:53], v[52:53], 0, s[72:73]
	v_add_f32_e32 v50, v50, v51
	global_store_dword v[52:53], v50, off
.LBB0_1905:
	s_or_b64 exec, exec, s[58:59]
	s_waitcnt vmcnt(7)
	v_lshlrev_b32_e32 v52, 16, v201
	v_and_b32_e32 v53, 0xffff0000, v201
	v_lshlrev_b32_e32 v54, 16, v202
	v_and_b32_e32 v55, 0xffff0000, v202
	v_pk_add_f32 v[48:49], v[48:49], v[52:53]
	v_pk_add_f32 v[52:53], v[42:43], v[54:55]
	v_lshl_add_u64 v[54:55], s[10:11], 0, v[100:101]
	v_lshlrev_b32_e32 v50, 16, v200
	v_and_b32_e32 v51, 0xffff0000, v200
	v_lshlrev_b32_e32 v56, 16, v203
	v_and_b32_e32 v57, 0xffff0000, v203
	v_lshl_add_u64 v[54:55], s[56:57], 1, v[54:55]
	v_pk_add_f32 v[46:47], v[46:47], v[50:51]
	v_pk_add_f32 v[50:51], v[44:45], v[56:57]
	v_lshl_add_u64 v[54:55], v[54:55], 0, s[18:19]
	v_cvt_pk_bf16_f32 v42, v46, v47
	v_cvt_pk_bf16_f32 v43, v48, v49
	v_cvt_pk_bf16_f32 v44, v52, v53
	v_cvt_pk_bf16_f32 v45, v50, v51
	v_lshl_add_u64 v[54:55], v[54:55], 0, v[0:1]
	global_store_dwordx4 v[54:55], v[42:45], off
	s_nop 1
	v_mul_f32_e32 v42, v47, v47
	v_mul_f32_e32 v43, v49, v49
	v_fmac_f32_e32 v42, v46, v46
	v_fmac_f32_e32 v43, v48, v48
	v_add_f32_e32 v42, v42, v43
	v_mul_f32_e32 v43, v53, v53
	v_fmac_f32_e32 v43, v52, v52
	v_add_f32_e32 v42, v43, v42
	v_mul_f32_e32 v43, v51, v51
	v_fmac_f32_e32 v43, v50, v50
	v_add_f32_e32 v50, v43, v42
	s_waitcnt vmcnt(7)
	v_lshlrev_b32_e32 v42, 16, v204
	v_and_b32_e32 v43, 0xffff0000, v204
	v_lshlrev_b32_e32 v44, 16, v205
	v_and_b32_e32 v45, 0xffff0000, v205
	v_lshlrev_b32_e32 v46, 16, v206
	v_and_b32_e32 v47, 0xffff0000, v206
	v_lshlrev_b32_e32 v48, 16, v207
	v_and_b32_e32 v49, 0xffff0000, v207
	v_pk_add_f32 v[40:41], v[40:41], v[44:45]
	v_pk_add_f32 v[38:39], v[38:39], v[42:43]
	v_pk_add_f32 v[42:43], v[36:37], v[48:49]
	v_pk_add_f32 v[44:45], v[34:35], v[46:47]
	v_cvt_pk_bf16_f32 v34, v38, v39
	v_cvt_pk_bf16_f32 v35, v40, v41
	v_cvt_pk_bf16_f32 v36, v44, v45
	v_cvt_pk_bf16_f32 v37, v42, v43
	global_store_dwordx4 v[54:55], v[34:37], off offset:256
	s_nop 1
	v_mul_f32_e32 v34, v39, v39
	v_mul_f32_e32 v35, v41, v41
	v_fmac_f32_e32 v34, v38, v38
	v_fmac_f32_e32 v35, v40, v40
	v_add_f32_e32 v34, v34, v35
	v_mul_f32_e32 v35, v45, v45
	v_fmac_f32_e32 v35, v44, v44
	v_add_f32_e32 v34, v35, v34
	v_mul_f32_e32 v35, v43, v43
	v_fmac_f32_e32 v35, v42, v42
	v_add_f32_e32 v34, v35, v34
	v_add_f32_e32 v34, v50, v34
	v_mov_b32_e32 v35, v34
	s_nop 1
	v_permlane32_swap_b32_e32 v34, v35
	v_add_f32_e32 v34, v34, v35
	v_mov_b32_e32 v35, v34
	s_nop 1
	v_permlane16_swap_b32_e32 v34, v35
	s_and_saveexec_b64 s[58:59], vcc
	s_cbranch_execz .LBB0_1907
	v_lshlrev_b64 v[36:37], 6, v[98:99]
	v_lshl_add_u64 v[36:37], s[12:13], 0, v[36:37]
	v_lshl_add_u64 v[36:37], s[54:55], 2, v[36:37]
	s_lshl_b32 s72, s45, 2
	s_mov_b32 s73, s19
	v_lshl_add_u64 v[36:37], v[36:37], 0, s[72:73]
	v_add_f32_e32 v34, v34, v35
	global_store_dword v[36:37], v34, off
; __device__ __forceinline__ u32x4 pack8(f32x4 a, f32x4 b) { u32x4 w; w.x = cvtpk(a[0], a[1]); w.y = cvtpk(a[2], a[3]); w.z = cvtpk(b[0], b[1]); w.w = cvtpk(b[2], b[3]); return w; }
;     __device__ __forceinline__ void operator()(AccRef acc, const Unit& u, int wr, int wc, int fr, int fq) const {
;     ...
;             for (int m = 0; m < 4; ++m) {
;                 const int row = u.pm * 256 + ai * 128 + wr * 64 + m * 16 + fr; float part = 0.f;
;                 const float sc = RS ? scale * rst[u.ui * 256 + ai * 128 + wr * 64 + m * 16 + fr] : scale;
; #pragma unroll
;                 for (int bj = 0; bj < 2; ++bj) {
;                     const size_t idx = (size_t)row * D + u.pn * 256 + bj * 128 + wc * 32 + 8 * fq;
;                     const u32x4 o4 = ow[m][bj];
;                     f32x4 v0, v1;
;                     v0[0] = __uint_as_float(o4.x << 16); v0[1] = __uint_as_float(o4.x & 0xffff0000u); v0[2] = __uint_as_float(o4.y << 16); v0[3] = __uint_as_float(o4.y & 0xffff0000u);
;                     v1[0] = __uint_as_float(o4.z << 16); v1[1] = __uint_as_float(o4.z & 0xffff0000u); v1[2] = __uint_as_float(o4.w << 16); v1[3] = __uint_as_float(o4.w & 0xffff0000u);
;                     v0 = v0 + acc[ai][bj][m][0] * sc; v1 = v1 + acc[ai][bj][m][1] * sc;
;                     *(u32x4*)(hb + idx) = pack8(v0, v1);
;                     part += (v0[0] * v0[0] + v0[1] * v0[1]) + (v0[2] * v0[2] + v0[3] * v0[3]) + (v1[0] * v1[0] + v1[1] * v1[1]) + (v1[2] * v1[2] + v1[3] * v1[3]);
;                 }
;                 part = fq_sum(part);
;                 if (fq == 0) ssn[(size_t)row * 16 + u.pn * 4 + wc] = part;
.LBB0_1907:
	s_or_b64 exec, exec, s[58:59]
	s_waitcnt vmcnt(7)
	v_lshlrev_b32_e32 v36, 16, v209
	v_and_b32_e32 v37, 0xffff0000, v209
	v_lshlrev_b32_e32 v38, 16, v210
	v_and_b32_e32 v39, 0xffff0000, v210
	v_pk_add_f32 v[32:33], v[32:33], v[36:37]
	v_pk_add_f32 v[36:37], v[26:27], v[38:39]
	v_lshl_add_u64 v[38:39], s[10:11], 0, v[96:97]
	v_lshlrev_b32_e32 v34, 16, v208
	v_and_b32_e32 v35, 0xffff0000, v208
	v_lshlrev_b32_e32 v40, 16, v211
	v_and_b32_e32 v41, 0xffff0000, v211
	v_lshl_add_u64 v[38:39], s[56:57], 1, v[38:39]
	v_pk_add_f32 v[30:31], v[30:31], v[34:35]
	v_pk_add_f32 v[34:35], v[28:29], v[40:41]
	v_lshl_add_u64 v[38:39], v[38:39], 0, s[18:19]
	v_cvt_pk_bf16_f32 v26, v30, v31
	v_cvt_pk_bf16_f32 v27, v32, v33
	v_cvt_pk_bf16_f32 v28, v36, v37
	v_cvt_pk_bf16_f32 v29, v34, v35
	v_lshl_add_u64 v[38:39], v[38:39], 0, v[0:1]
	global_store_dwordx4 v[38:39], v[26:29], off
	s_nop 1
	v_mul_f32_e32 v26, v31, v31
	v_mul_f32_e32 v27, v33, v33
	v_fmac_f32_e32 v26, v30, v30
	v_fmac_f32_e32 v27, v32, v32
	v_add_f32_e32 v26, v26, v27
	v_mul_f32_e32 v27, v37, v37
	v_fmac_f32_e32 v27, v36, v36
	v_add_f32_e32 v26, v27, v26
	v_mul_f32_e32 v27, v35, v35
	v_fmac_f32_e32 v27, v34, v34
	v_add_f32_e32 v34, v27, v26
	s_waitcnt vmcnt(7)
	v_lshlrev_b32_e32 v26, 16, v212
	v_and_b32_e32 v27, 0xffff0000, v212
	v_lshlrev_b32_e32 v28, 16, v213
	v_and_b32_e32 v29, 0xffff0000, v213
	v_lshlrev_b32_e32 v30, 16, v214
	v_and_b32_e32 v31, 0xffff0000, v214
	v_lshlrev_b32_e32 v32, 16, v215
	v_and_b32_e32 v33, 0xffff0000, v215
	v_pk_add_f32 v[24:25], v[24:25], v[28:29]
	v_pk_add_f32 v[22:23], v[22:23], v[26:27]
	v_pk_add_f32 v[26:27], v[20:21], v[32:33]
	v_pk_add_f32 v[28:29], v[18:19], v[30:31]
	v_cvt_pk_bf16_f32 v18, v22, v23
	v_cvt_pk_bf16_f32 v19, v24, v25
	v_cvt_pk_bf16_f32 v20, v28, v29
	v_cvt_pk_bf16_f32 v21, v26, v27
	global_store_dwordx4 v[38:39], v[18:21], off offset:256
	s_nop 1
	v_mul_f32_e32 v18, v23, v23
	v_mul_f32_e32 v19, v25, v25
	v_fmac_f32_e32 v18, v22, v22
	v_fmac_f32_e32 v19, v24, v24
	v_add_f32_e32 v18, v18, v19
	v_mul_f32_e32 v19, v29, v29
	v_fmac_f32_e32 v19, v28, v28
	v_add_f32_e32 v18, v19, v18
	v_mul_f32_e32 v19, v27, v27
	v_fmac_f32_e32 v19, v26, v26
	v_add_f32_e32 v18, v19, v18
	v_add_f32_e32 v18, v34, v18
	v_mov_b32_e32 v19, v18
	s_nop 1
	v_permlane32_swap_b32_e32 v18, v19
	v_add_f32_e32 v18, v18, v19
	v_mov_b32_e32 v19, v18
	s_nop 1
	v_permlane16_swap_b32_e32 v18, v19
	s_and_saveexec_b64 s[58:59], vcc
	s_cbranch_execz .LBB0_1909
	v_lshlrev_b64 v[20:21], 6, v[94:95]
	v_lshl_add_u64 v[20:21], s[12:13], 0, v[20:21]
	v_lshl_add_u64 v[20:21], s[54:55], 2, v[20:21]
	s_lshl_b32 s72, s45, 2
	s_mov_b32 s73, s19
	v_lshl_add_u64 v[20:21], v[20:21], 0, s[72:73]
	v_add_f32_e32 v18, v18, v19
	global_store_dword v[20:21], v18, off
.LBB0_1909:
	s_or_b64 exec, exec, s[58:59]
	s_waitcnt vmcnt(7)
	v_lshlrev_b32_e32 v20, 16, v221
	v_and_b32_e32 v21, 0xffff0000, v221
	v_lshlrev_b32_e32 v22, 16, v222
	v_and_b32_e32 v23, 0xffff0000, v222
	v_pk_add_f32 v[16:17], v[16:17], v[20:21]
	v_pk_add_f32 v[20:21], v[10:11], v[22:23]
	v_lshl_add_u64 v[22:23], s[10:11], 0, v[92:93]
	v_lshlrev_b32_e32 v18, 16, v220
	v_and_b32_e32 v19, 0xffff0000, v220
	v_lshlrev_b32_e32 v24, 16, v223
	v_and_b32_e32 v25, 0xffff0000, v223
	v_lshl_add_u64 v[22:23], s[56:57], 1, v[22:23]
	v_pk_add_f32 v[14:15], v[14:15], v[18:19]
	v_pk_add_f32 v[18:19], v[12:13], v[24:25]
	v_lshl_add_u64 v[22:23], v[22:23], 0, s[18:19]
	v_cvt_pk_bf16_f32 v10, v14, v15
	v_cvt_pk_bf16_f32 v11, v16, v17
	v_cvt_pk_bf16_f32 v12, v20, v21
	v_cvt_pk_bf16_f32 v13, v18, v19
	v_lshl_add_u64 v[22:23], v[22:23], 0, v[0:1]
	global_store_dwordx4 v[22:23], v[10:13], off
	v_mul_f32_e32 v0, v15, v15
	v_fmac_f32_e32 v0, v14, v14
	v_mul_f32_e32 v10, v17, v17
	v_fmac_f32_e32 v10, v16, v16
	v_add_f32_e32 v0, v0, v10
	v_mul_f32_e32 v10, v21, v21
	v_fmac_f32_e32 v10, v20, v20
	v_add_f32_e32 v0, v10, v0
	v_mul_f32_e32 v10, v19, v19
	v_fmac_f32_e32 v10, v18, v18
	v_add_f32_e32 v0, v10, v0
	s_waitcnt vmcnt(7)
	v_lshlrev_b32_e32 v10, 16, v238
	v_and_b32_e32 v11, 0xffff0000, v238
	v_lshlrev_b32_e32 v12, 16, v239
	v_and_b32_e32 v13, 0xffff0000, v239
	v_lshlrev_b32_e32 v14, 16, v240
	v_and_b32_e32 v15, 0xffff0000, v240
	v_lshlrev_b32_e32 v16, 16, v241
	v_and_b32_e32 v17, 0xffff0000, v241
	v_pk_add_f32 v[8:9], v[8:9], v[12:13]
	v_pk_add_f32 v[6:7], v[6:7], v[10:11]
	v_pk_add_f32 v[10:11], v[4:5], v[16:17]
	v_pk_add_f32 v[12:13], v[2:3], v[14:15]
	v_cvt_pk_bf16_f32 v2, v6, v7
	v_cvt_pk_bf16_f32 v3, v8, v9
	v_cvt_pk_bf16_f32 v4, v12, v13
	v_cvt_pk_bf16_f32 v5, v10, v11
	global_store_dwordx4 v[22:23], v[2:5], off offset:256
	s_nop 1
	v_mul_f32_e32 v2, v7, v7
	v_mul_f32_e32 v3, v9, v9
	v_fmac_f32_e32 v2, v6, v6
	v_fmac_f32_e32 v3, v8, v8
	v_add_f32_e32 v2, v2, v3
	v_mul_f32_e32 v3, v13, v13
	v_fmac_f32_e32 v3, v12, v12
	v_add_f32_e32 v2, v3, v2
	v_mul_f32_e32 v3, v11, v11
	v_fmac_f32_e32 v3, v10, v10
	v_add_f32_e32 v2, v3, v2
	v_add_f32_e32 v0, v0, v2
	v_mov_b32_e32 v2, v0
	s_nop 1
	v_permlane32_swap_b32_e32 v0, v2
	v_add_f32_e32 v0, v0, v2
	v_mov_b32_e32 v2, v0
	s_nop 1
	v_permlane16_swap_b32_e32 v0, v2
	s_and_saveexec_b64 s[56:57], vcc
	s_cbranch_execz .LBB0_1911
	v_lshlrev_b64 v[4:5], 6, v[90:91]
	v_lshl_add_u64 v[4:5], s[12:13], 0, v[4:5]
	v_lshl_add_u64 v[4:5], s[54:55], 2, v[4:5]
	s_lshl_b32 s18, s45, 2
	v_lshl_add_u64 v[4:5], v[4:5], 0, s[18:19]
	v_add_f32_e32 v0, v0, v2
	global_store_dword v[4:5], v0, off

; __device__ __forceinline__ u32x4 pack8(f32x4 a, f32x4 b) { u32x4 w; w.x = cvtpk(a[0], a[1]); w.y = cvtpk(a[2], a[3]); w.z = cvtpk(b[0], b[1]); w.w = cvtpk(b[2], b[3]); return w; }
;     __device__ __forceinline__ void operator()(AccRef acc, const Unit& u, int wr, int wc, int fr, int fq) const {
; #pragma unroll
;         for (int ai = 0; ai < 2; ++ai) {
;             u32x4 ow[4][2];
; #pragma unroll
;             for (int m = 0; m < 4; ++m)
; #pragma unroll
;                 for (int bj = 0; bj < 2; ++bj)
;                     ow[m][bj] = *(const u32x4*)(hb + (size_t)(u.pm * 256 + ai * 128 + wr * 64 + m * 16 + fr) * D + u.pn * 256 + bj * 128 + wc * 32 + 8 * fq);
;             __builtin_amdgcn_sched_barrier(0);
; #pragma unroll
;             for (int m = 0; m < 4; ++m) {
;                 const int row = u.pm * 256 + ai * 128 + wr * 64 + m * 16 + fr; float part = 0.f;
;                 const float sc = RS ? scale * rst[u.ui * 256 + ai * 128 + wr * 64 + m * 16 + fr] : scale;
; #pragma unroll
;                 for (int bj = 0; bj < 2; ++bj) {
;                     const size_t idx = (size_t)row * D + u.pn * 256 + bj * 128 + wc * 32 + 8 * fq;
;                     const u32x4 o4 = ow[m][bj];
;                     f32x4 v0, v1;
;                     v0[0] = __uint_as_float(o4.x << 16); v0[1] = __uint_as_float(o4.x & 0xffff0000u); v0[2] = __uint_as_float(o4.y << 16); v0[3] = __uint_as_float(o4.y & 0xffff0000u);
;                     v1[0] = __uint_as_float(o4.z << 16); v1[1] = __uint_as_float(o4.z & 0xffff0000u); v1[2] = __uint_as_float(o4.w << 16); v1[3] = __uint_as_float(o4.w & 0xffff0000u);
;                     v0 = v0 + acc[ai][bj][m][0] * sc; v1 = v1 + acc[ai][bj][m][1] * sc;
;                     *(u32x4*)(hb + idx) = pack8(v0, v1);
;                     part += (v0[0] * v0[0] + v0[1] * v0[1]) + (v0[2] * v0[2] + v0[3] * v0[3]) + (v1[0] * v1[0] + v1[1] * v1[1]) + (v1[2] * v1[2] + v1[3] * v1[3]);
;                 }
;                 part = fq_sum(part);
;                 if (fq == 0) ssn[(size_t)row * 16 + u.pn * 4 + wc] = part;
.LBB0_2085:
	s_lshl_b32 s54, s72, 8
	s_lshl_b32 s17, s73, 8
	s_ashr_i32 s55, s54, 31
	s_lshl_b32 s52, s72, 2
	v_mov_b32_e32 v0, v236
	s_add_i32 s17, s17, s58
	s_ashr_i32 s53, s52, 31
	s_lshl_b64 s[56:57], s[54:55], 1
	s_add_u32 s72, s67, s56
	v_bfe_u32 v170, v0, 4, 2
	v_and_or_b32 v154, v0, 15, s17
	s_addc_u32 s73, s68, s57
	v_lshlrev_b32_e32 v0, 4, v170
	v_ashrrev_i32_e32 v155, 31, v154
	v_or_b32_e32 v166, 16, v154
	v_lshl_add_u64 v[156:157], s[72:73], 0, v[0:1]
	v_lshlrev_b64 v[180:181], 11, v[154:155]
	v_ashrrev_i32_e32 v167, 31, v166
	v_or_b32_e32 v162, 32, v154
	v_lshl_add_u64 v[130:131], v[156:157], 0, v[180:181]
	v_lshlrev_b64 v[168:169], 11, v[166:167]
	v_ashrrev_i32_e32 v163, 31, v162
	v_or_b32_e32 v158, 48, v154
	global_load_dwordx4 v[172:175], v[130:131], off
	global_load_dwordx4 v[176:179], v[130:131], off offset:256
	v_lshl_add_u64 v[130:131], v[156:157], 0, v[168:169]
	v_lshlrev_b64 v[164:165], 11, v[162:163]
	v_ashrrev_i32_e32 v159, 31, v158
	global_load_dwordx4 v[150:153], v[130:131], off
	global_load_dwordx4 v[146:149], v[130:131], off offset:256
	v_lshl_add_u64 v[130:131], v[156:157], 0, v[164:165]
	v_lshlrev_b64 v[160:161], 11, v[158:159]
	global_load_dwordx4 v[142:145], v[130:131], off
	global_load_dwordx4 v[138:141], v[130:131], off offset:256
	v_lshl_add_u64 v[130:131], v[156:157], 0, v[160:161]
	global_load_dwordx4 v[134:137], v[130:131], off
	s_nop 0
	global_load_dwordx4 v[130:133], v[130:131], off offset:256
	v_mov_b32_e32 v190, 0x40000
	v_mov_b32_e32 v191, 0
	v_lshl_add_u64 v[216:217], v[190:191], 0, v[180:181]
	v_lshl_add_u64 v[216:217], v[156:157], 0, v[216:217]
	global_load_dwordx4 v[186:189], v[216:217], off
	global_load_dwordx4 v[196:199], v[216:217], off offset:256
	v_lshl_add_u64 v[216:217], v[190:191], 0, v[168:169]
	v_lshl_add_u64 v[216:217], v[156:157], 0, v[216:217]
	global_load_dwordx4 v[200:203], v[216:217], off
	global_load_dwordx4 v[204:207], v[216:217], off offset:256
	v_lshl_add_u64 v[216:217], v[190:191], 0, v[164:165]
	v_lshl_add_u64 v[216:217], v[156:157], 0, v[216:217]
	global_load_dwordx4 v[208:211], v[216:217], off
	global_load_dwordx4 v[212:215], v[216:217], off offset:256
	v_lshl_add_u64 v[216:217], v[190:191], 0, v[160:161]
	v_lshl_add_u64 v[216:217], v[156:157], 0, v[216:217]
	global_load_dwordx4 v[220:223], v[216:217], off
	global_load_dwordx4 v[238:241], v[216:217], off offset:256
	v_cmp_eq_u32_e32 vcc, 0, v170
	v_lshl_add_u64 v[180:181], s[10:11], 0, v[180:181]
	s_waitcnt vmcnt(0)
	v_lshlrev_b32_e32 v182, 16, v172
	v_and_b32_e32 v183, 0xffff0000, v172
	v_lshlrev_b32_e32 v172, 16, v173
	v_and_b32_e32 v173, 0xffff0000, v173
	v_lshlrev_b32_e32 v184, 16, v174
	v_and_b32_e32 v185, 0xffff0000, v174
	v_lshlrev_b32_e32 v174, 16, v175
	v_and_b32_e32 v175, 0xffff0000, v175
	v_lshl_add_u64 v[180:181], v[180:181], 0, s[56:57]
	s_lshl_b32 s18, s60, 1
	v_pk_fma_f32 v[128:129], v[128:129], 0.5, v[172:173] op_sel_hi:[1,0,1]
	v_pk_fma_f32 v[126:127], v[126:127], 0.5, v[182:183] op_sel_hi:[1,0,1]
	v_pk_fma_f32 v[172:173], v[124:125], 0.5, v[174:175] op_sel_hi:[1,0,1]
	v_pk_fma_f32 v[174:175], v[122:123], 0.5, v[184:185] op_sel_hi:[1,0,1]
	v_lshl_add_u64 v[180:181], v[180:181], 0, s[18:19]
	v_cvt_pk_bf16_f32 v122, v126, v127
	v_cvt_pk_bf16_f32 v123, v128, v129
	v_cvt_pk_bf16_f32 v124, v174, v175
	v_cvt_pk_bf16_f32 v125, v172, v173
	v_lshl_add_u64 v[180:181], v[180:181], 0, v[0:1]
	global_store_dwordx4 v[180:181], v[122:125], off
	v_mul_f32_e32 v0, v127, v127
	v_fmac_f32_e32 v0, v126, v126
	v_mul_f32_e32 v122, v129, v129
	v_fmac_f32_e32 v122, v128, v128
	v_add_f32_e32 v0, v0, v122
	v_mul_f32_e32 v122, v175, v175
	v_fmac_f32_e32 v122, v174, v174
	v_add_f32_e32 v0, v122, v0
	v_mul_f32_e32 v122, v173, v173
	v_fmac_f32_e32 v122, v172, v172
	v_add_f32_e32 v0, v122, v0
	v_lshlrev_b32_e32 v122, 16, v176
	v_and_b32_e32 v123, 0xffff0000, v176
	v_lshlrev_b32_e32 v124, 16, v177
	v_and_b32_e32 v125, 0xffff0000, v177
	v_lshlrev_b32_e32 v126, 16, v178
	v_and_b32_e32 v127, 0xffff0000, v178
	v_lshlrev_b32_e32 v128, 16, v179
	v_and_b32_e32 v129, 0xffff0000, v179
	v_pk_fma_f32 v[120:121], v[120:121], 0.5, v[124:125] op_sel_hi:[1,0,1]
	v_pk_fma_f32 v[118:119], v[118:119], 0.5, v[122:123] op_sel_hi:[1,0,1]
	v_pk_fma_f32 v[122:123], v[116:117], 0.5, v[128:129] op_sel_hi:[1,0,1]
	v_pk_fma_f32 v[124:125], v[114:115], 0.5, v[126:127] op_sel_hi:[1,0,1]
	v_cvt_pk_bf16_f32 v114, v118, v119
	v_cvt_pk_bf16_f32 v115, v120, v121
	v_cvt_pk_bf16_f32 v116, v124, v125
	v_cvt_pk_bf16_f32 v117, v122, v123
	global_store_dwordx4 v[180:181], v[114:117], off offset:256
	s_nop 1
	v_mul_f32_e32 v114, v119, v119
	v_mul_f32_e32 v115, v121, v121
	v_fmac_f32_e32 v114, v118, v118
	v_fmac_f32_e32 v115, v120, v120
	v_add_f32_e32 v114, v114, v115
	v_mul_f32_e32 v115, v125, v125
	v_fmac_f32_e32 v115, v124, v124
	v_add_f32_e32 v114, v115, v114
	v_mul_f32_e32 v115, v123, v123
	v_fmac_f32_e32 v115, v122, v122
	v_add_f32_e32 v114, v115, v114
	v_add_f32_e32 v0, v0, v114
	v_mov_b32_e32 v114, v0
	s_nop 1
	v_permlane32_swap_b32_e32 v0, v114
	v_add_f32_e32 v0, v0, v114
	v_mov_b32_e32 v114, v0
	s_nop 1
	v_permlane16_swap_b32_e32 v0, v114
	s_and_saveexec_b64 s[56:57], vcc
	s_cbranch_execz .LBB0_2087
	v_lshlrev_b64 v[116:117], 6, v[154:155]
	v_lshl_add_u64 v[116:117], s[12:13], 0, v[116:117]
	v_lshl_add_u64 v[116:117], s[52:53], 2, v[116:117]
	s_lshl_b32 s72, s47, 2
	s_mov_b32 s73, s19
	v_lshl_add_u64 v[116:117], v[116:117], 0, s[72:73]
	v_add_f32_e32 v0, v0, v114
	global_store_dword v[116:117], v0, off

; __device__ __forceinline__ u32x4 pack8(f32x4 a, f32x4 b) { u32x4 w; w.x = cvtpk(a[0], a[1]); w.y = cvtpk(a[2], a[3]); w.z = cvtpk(b[0], b[1]); w.w = cvtpk(b[2], b[3]); return w; }
;     __device__ __forceinline__ void operator()(AccRef acc, const Unit& u, int wr, int wc, int fr, int fq) const {
;     ...
;             for (int m = 0; m < 4; ++m) {
;                 const int row = u.pm * 256 + ai * 128 + wr * 64 + m * 16 + fr; float part = 0.f;
;                 const float sc = RS ? scale * rst[u.ui * 256 + ai * 128 + wr * 64 + m * 16 + fr] : scale;
; #pragma unroll
;                 for (int bj = 0; bj < 2; ++bj) {
;                     const size_t idx = (size_t)row * D + u.pn * 256 + bj * 128 + wc * 32 + 8 * fq;
;                     const u32x4 o4 = ow[m][bj];
;                     f32x4 v0, v1;
;                     v0[0] = __uint_as_float(o4.x << 16); v0[1] = __uint_as_float(o4.x & 0xffff0000u); v0[2] = __uint_as_float(o4.y << 16); v0[3] = __uint_as_float(o4.y & 0xffff0000u);
;                     v1[0] = __uint_as_float(o4.z << 16); v1[1] = __uint_as_float(o4.z & 0xffff0000u); v1[2] = __uint_as_float(o4.w << 16); v1[3] = __uint_as_float(o4.w & 0xffff0000u);
;                     v0 = v0 + acc[ai][bj][m][0] * sc; v1 = v1 + acc[ai][bj][m][1] * sc;
;                     *(u32x4*)(hb + idx) = pack8(v0, v1);
;                     part += (v0[0] * v0[0] + v0[1] * v0[1]) + (v0[2] * v0[2] + v0[3] * v0[3]) + (v1[0] * v1[0] + v1[1] * v1[1]) + (v1[2] * v1[2] + v1[3] * v1[3]);
;                 }
;                 part = fq_sum(part);
;                 if (fq == 0) ssn[(size_t)row * 16 + u.pn * 4 + wc] = part;
.LBB0_2093:
	s_or_b64 exec, exec, s[56:57]
	v_add_u32_e32 v102, 0x80, v154
	v_ashrrev_i32_e32 v103, 31, v102
	v_add_u32_e32 v98, 0x90, v154
	v_lshlrev_b64 v[112:113], 11, v[102:103]
	v_ashrrev_i32_e32 v99, 31, v98
	v_add_u32_e32 v94, 0xa0, v154
	v_lshl_add_u64 v[66:67], v[156:157], 0, v[112:113]
	v_lshlrev_b64 v[100:101], 11, v[98:99]
	v_ashrrev_i32_e32 v95, 31, v94
	v_add_u32_e32 v90, 0xb0, v154
	v_lshl_add_u64 v[66:67], v[156:157], 0, v[100:101]
	v_lshlrev_b64 v[96:97], 11, v[94:95]
	v_ashrrev_i32_e32 v91, 31, v90
	v_lshl_add_u64 v[66:67], v[156:157], 0, v[96:97]
	v_lshlrev_b64 v[92:93], 11, v[90:91]
	v_lshl_add_u64 v[66:67], v[156:157], 0, v[92:93]
	s_nop 0
	v_lshl_add_u64 v[112:113], s[10:11], 0, v[112:113]
	s_waitcnt vmcnt(7)
	v_lshlrev_b32_e32 v114, 16, v186
	v_and_b32_e32 v115, 0xffff0000, v186
	v_lshlrev_b32_e32 v104, 16, v187
	v_and_b32_e32 v105, 0xffff0000, v187
	v_lshlrev_b32_e32 v116, 16, v188
	v_and_b32_e32 v117, 0xffff0000, v188
	v_lshlrev_b32_e32 v106, 16, v189
	v_and_b32_e32 v107, 0xffff0000, v189
	v_lshl_add_u64 v[112:113], s[54:55], 1, v[112:113]
	v_pk_fma_f32 v[64:65], v[64:65], 0.5, v[104:105] op_sel_hi:[1,0,1]
	v_pk_fma_f32 v[62:63], v[62:63], 0.5, v[114:115] op_sel_hi:[1,0,1]
	v_pk_fma_f32 v[104:105], v[60:61], 0.5, v[106:107] op_sel_hi:[1,0,1]
	v_pk_fma_f32 v[106:107], v[58:59], 0.5, v[116:117] op_sel_hi:[1,0,1]
	v_lshl_add_u64 v[112:113], v[112:113], 0, s[18:19]
	v_cvt_pk_bf16_f32 v58, v62, v63
	v_cvt_pk_bf16_f32 v59, v64, v65
	v_cvt_pk_bf16_f32 v60, v106, v107
	v_cvt_pk_bf16_f32 v61, v104, v105
	v_lshl_add_u64 v[112:113], v[112:113], 0, v[0:1]
	global_store_dwordx4 v[112:113], v[58:61], off
	s_nop 1
	v_mul_f32_e32 v58, v63, v63
	v_mul_f32_e32 v59, v65, v65
	v_fmac_f32_e32 v58, v62, v62
	v_fmac_f32_e32 v59, v64, v64
	v_add_f32_e32 v58, v58, v59
	v_mul_f32_e32 v59, v107, v107
	v_fmac_f32_e32 v59, v106, v106
	v_add_f32_e32 v58, v59, v58
	v_mul_f32_e32 v59, v105, v105
	v_fmac_f32_e32 v59, v104, v104
	v_add_f32_e32 v104, v59, v58
	s_waitcnt vmcnt(7)
	v_lshlrev_b32_e32 v58, 16, v196
	v_and_b32_e32 v59, 0xffff0000, v196
	v_lshlrev_b32_e32 v60, 16, v197
	v_and_b32_e32 v61, 0xffff0000, v197
	v_lshlrev_b32_e32 v62, 16, v198
	v_and_b32_e32 v63, 0xffff0000, v198
	v_lshlrev_b32_e32 v64, 16, v199
	v_and_b32_e32 v65, 0xffff0000, v199
	v_pk_fma_f32 v[56:57], v[56:57], 0.5, v[60:61] op_sel_hi:[1,0,1]
	v_pk_fma_f32 v[54:55], v[54:55], 0.5, v[58:59] op_sel_hi:[1,0,1]
	v_pk_fma_f32 v[58:59], v[52:53], 0.5, v[64:65] op_sel_hi:[1,0,1]
	v_pk_fma_f32 v[60:61], v[50:51], 0.5, v[62:63] op_sel_hi:[1,0,1]
	v_cvt_pk_bf16_f32 v50, v54, v55
	v_cvt_pk_bf16_f32 v51, v56, v57
	v_cvt_pk_bf16_f32 v52, v60, v61
	v_cvt_pk_bf16_f32 v53, v58, v59
	global_store_dwordx4 v[112:113], v[50:53], off offset:256
	s_nop 1
	v_mul_f32_e32 v50, v55, v55
	v_mul_f32_e32 v51, v57, v57
	v_fmac_f32_e32 v50, v54, v54
	v_fmac_f32_e32 v51, v56, v56
	v_add_f32_e32 v50, v50, v51
	v_mul_f32_e32 v51, v61, v61
	v_fmac_f32_e32 v51, v60, v60
	v_add_f32_e32 v50, v51, v50
	v_mul_f32_e32 v51, v59, v59
	v_fmac_f32_e32 v51, v58, v58
	v_add_f32_e32 v50, v51, v50
	v_add_f32_e32 v50, v104, v50
	v_mov_b32_e32 v51, v50
	s_nop 1
	v_permlane32_swap_b32_e32 v50, v51
	v_add_f32_e32 v50, v50, v51
	v_mov_b32_e32 v51, v50
	s_nop 1
	v_permlane16_swap_b32_e32 v50, v51
	s_and_saveexec_b64 s[56:57], vcc
	s_cbranch_execz .LBB0_2095
	v_lshlrev_b64 v[52:53], 6, v[102:103]
	v_lshl_add_u64 v[52:53], s[12:13], 0, v[52:53]
	v_lshl_add_u64 v[52:53], s[52:53], 2, v[52:53]
	s_lshl_b32 s72, s47, 2
	s_mov_b32 s73, s19
	v_lshl_add_u64 v[52:53], v[52:53], 0, s[72:73]
	v_add_f32_e32 v50, v50, v51
	global_store_dword v[52:53], v50, off
.LBB0_2095:
	s_or_b64 exec, exec, s[56:57]
	s_waitcnt vmcnt(7)
	v_lshlrev_b32_e32 v52, 16, v201
	v_and_b32_e32 v53, 0xffff0000, v201
	v_lshlrev_b32_e32 v54, 16, v202
	v_and_b32_e32 v55, 0xffff0000, v202
	v_pk_fma_f32 v[48:49], v[48:49], 0.5, v[52:53] op_sel_hi:[1,0,1]
	v_pk_fma_f32 v[52:53], v[42:43], 0.5, v[54:55] op_sel_hi:[1,0,1]
	v_lshl_add_u64 v[54:55], s[10:11], 0, v[100:101]
	v_lshlrev_b32_e32 v50, 16, v200
	v_and_b32_e32 v51, 0xffff0000, v200
	v_lshlrev_b32_e32 v56, 16, v203
	v_and_b32_e32 v57, 0xffff0000, v203
	v_lshl_add_u64 v[54:55], s[54:55], 1, v[54:55]
	v_pk_fma_f32 v[46:47], v[46:47], 0.5, v[50:51] op_sel_hi:[1,0,1]
	v_pk_fma_f32 v[50:51], v[44:45], 0.5, v[56:57] op_sel_hi:[1,0,1]
	v_lshl_add_u64 v[54:55], v[54:55], 0, s[18:19]
	v_cvt_pk_bf16_f32 v42, v46, v47
	v_cvt_pk_bf16_f32 v43, v48, v49
	v_cvt_pk_bf16_f32 v44, v52, v53
	v_cvt_pk_bf16_f32 v45, v50, v51
	v_lshl_add_u64 v[54:55], v[54:55], 0, v[0:1]
	global_store_dwordx4 v[54:55], v[42:45], off
	s_nop 1
	v_mul_f32_e32 v42, v47, v47
	v_mul_f32_e32 v43, v49, v49
	v_fmac_f32_e32 v42, v46, v46
	v_fmac_f32_e32 v43, v48, v48
	v_add_f32_e32 v42, v42, v43
	v_mul_f32_e32 v43, v53, v53
	v_fmac_f32_e32 v43, v52, v52
	v_add_f32_e32 v42, v43, v42
	v_mul_f32_e32 v43, v51, v51
	v_fmac_f32_e32 v43, v50, v50
	v_add_f32_e32 v50, v43, v42
	s_waitcnt vmcnt(7)
	v_lshlrev_b32_e32 v42, 16, v204
	v_and_b32_e32 v43, 0xffff0000, v204
	v_lshlrev_b32_e32 v44, 16, v205
	v_and_b32_e32 v45, 0xffff0000, v205
	v_lshlrev_b32_e32 v46, 16, v206
	v_and_b32_e32 v47, 0xffff0000, v206
	v_lshlrev_b32_e32 v48, 16, v207
	v_and_b32_e32 v49, 0xffff0000, v207
	v_pk_fma_f32 v[40:41], v[40:41], 0.5, v[44:45] op_sel_hi:[1,0,1]
	v_pk_fma_f32 v[38:39], v[38:39], 0.5, v[42:43] op_sel_hi:[1,0,1]
	v_pk_fma_f32 v[42:43], v[36:37], 0.5, v[48:49] op_sel_hi:[1,0,1]
	v_pk_fma_f32 v[44:45], v[34:35], 0.5, v[46:47] op_sel_hi:[1,0,1]
	v_cvt_pk_bf16_f32 v34, v38, v39
	v_cvt_pk_bf16_f32 v35, v40, v41
	v_cvt_pk_bf16_f32 v36, v44, v45
	v_cvt_pk_bf16_f32 v37, v42, v43
	global_store_dwordx4 v[54:55], v[34:37], off offset:256
	s_nop 1
	v_mul_f32_e32 v34, v39, v39
	v_mul_f32_e32 v35, v41, v41
	v_fmac_f32_e32 v34, v38, v38
	v_fmac_f32_e32 v35, v40, v40
	v_add_f32_e32 v34, v34, v35
	v_mul_f32_e32 v35, v45, v45
	v_fmac_f32_e32 v35, v44, v44
	v_add_f32_e32 v34, v35, v34
	v_mul_f32_e32 v35, v43, v43
	v_fmac_f32_e32 v35, v42, v42
	v_add_f32_e32 v34, v35, v34
	v_add_f32_e32 v34, v50, v34
	v_mov_b32_e32 v35, v34
	s_nop 1
	v_permlane32_swap_b32_e32 v34, v35
	v_add_f32_e32 v34, v34, v35
	v_mov_b32_e32 v35, v34
	s_nop 1
	v_permlane16_swap_b32_e32 v34, v35
	s_and_saveexec_b64 s[56:57], vcc
	s_cbranch_execz .LBB0_2097
	v_lshlrev_b64 v[36:37], 6, v[98:99]
	v_lshl_add_u64 v[36:37], s[12:13], 0, v[36:37]
	v_lshl_add_u64 v[36:37], s[52:53], 2, v[36:37]
	s_lshl_b32 s72, s47, 2
	s_mov_b32 s73, s19
	v_lshl_add_u64 v[36:37], v[36:37], 0, s[72:73]
	v_add_f32_e32 v34, v34, v35
	global_store_dword v[36:37], v34, off
; __device__ __forceinline__ u32x4 pack8(f32x4 a, f32x4 b) { u32x4 w; w.x = cvtpk(a[0], a[1]); w.y = cvtpk(a[2], a[3]); w.z = cvtpk(b[0], b[1]); w.w = cvtpk(b[2], b[3]); return w; }
;     __device__ __forceinline__ void operator()(AccRef acc, const Unit& u, int wr, int wc, int fr, int fq) const {
;     ...
;             for (int m = 0; m < 4; ++m) {
;                 const int row = u.pm * 256 + ai * 128 + wr * 64 + m * 16 + fr; float part = 0.f;
;                 const float sc = RS ? scale * rst[u.ui * 256 + ai * 128 + wr * 64 + m * 16 + fr] : scale;
; #pragma unroll
;                 for (int bj = 0; bj < 2; ++bj) {
;                     const size_t idx = (size_t)row * D + u.pn * 256 + bj * 128 + wc * 32 + 8 * fq;
;                     const u32x4 o4 = ow[m][bj];
;                     f32x4 v0, v1;
;                     v0[0] = __uint_as_float(o4.x << 16); v0[1] = __uint_as_float(o4.x & 0xffff0000u); v0[2] = __uint_as_float(o4.y << 16); v0[3] = __uint_as_float(o4.y & 0xffff0000u);
;                     v1[0] = __uint_as_float(o4.z << 16); v1[1] = __uint_as_float(o4.z & 0xffff0000u); v1[2] = __uint_as_float(o4.w << 16); v1[3] = __uint_as_float(o4.w & 0xffff0000u);
;                     v0 = v0 + acc[ai][bj][m][0] * sc; v1 = v1 + acc[ai][bj][m][1] * sc;
;                     *(u32x4*)(hb + idx) = pack8(v0, v1);
;                     part += (v0[0] * v0[0] + v0[1] * v0[1]) + (v0[2] * v0[2] + v0[3] * v0[3]) + (v1[0] * v1[0] + v1[1] * v1[1]) + (v1[2] * v1[2] + v1[3] * v1[3]);
;                 }
;                 part = fq_sum(part);
;                 if (fq == 0) ssn[(size_t)row * 16 + u.pn * 4 + wc] = part;
.LBB0_2097:
	s_or_b64 exec, exec, s[56:57]
	s_waitcnt vmcnt(7)
	v_lshlrev_b32_e32 v36, 16, v209
	v_and_b32_e32 v37, 0xffff0000, v209
	v_lshlrev_b32_e32 v38, 16, v210
	v_and_b32_e32 v39, 0xffff0000, v210
	v_pk_fma_f32 v[32:33], v[32:33], 0.5, v[36:37] op_sel_hi:[1,0,1]
	v_pk_fma_f32 v[36:37], v[26:27], 0.5, v[38:39] op_sel_hi:[1,0,1]
	v_lshl_add_u64 v[38:39], s[10:11], 0, v[96:97]
	v_lshlrev_b32_e32 v34, 16, v208
	v_and_b32_e32 v35, 0xffff0000, v208
	v_lshlrev_b32_e32 v40, 16, v211
	v_and_b32_e32 v41, 0xffff0000, v211
	v_lshl_add_u64 v[38:39], s[54:55], 1, v[38:39]
	v_pk_fma_f32 v[30:31], v[30:31], 0.5, v[34:35] op_sel_hi:[1,0,1]
	v_pk_fma_f32 v[34:35], v[28:29], 0.5, v[40:41] op_sel_hi:[1,0,1]
	v_lshl_add_u64 v[38:39], v[38:39], 0, s[18:19]
	v_cvt_pk_bf16_f32 v26, v30, v31
	v_cvt_pk_bf16_f32 v27, v32, v33
	v_cvt_pk_bf16_f32 v28, v36, v37
	v_cvt_pk_bf16_f32 v29, v34, v35
	v_lshl_add_u64 v[38:39], v[38:39], 0, v[0:1]
	global_store_dwordx4 v[38:39], v[26:29], off
	s_nop 1
	v_mul_f32_e32 v26, v31, v31
	v_mul_f32_e32 v27, v33, v33
	v_fmac_f32_e32 v26, v30, v30
	v_fmac_f32_e32 v27, v32, v32
	v_add_f32_e32 v26, v26, v27
	v_mul_f32_e32 v27, v37, v37
	v_fmac_f32_e32 v27, v36, v36
	v_add_f32_e32 v26, v27, v26
	v_mul_f32_e32 v27, v35, v35
	v_fmac_f32_e32 v27, v34, v34
	v_add_f32_e32 v34, v27, v26
	s_waitcnt vmcnt(7)
	v_lshlrev_b32_e32 v26, 16, v212
	v_and_b32_e32 v27, 0xffff0000, v212
	v_lshlrev_b32_e32 v28, 16, v213
	v_and_b32_e32 v29, 0xffff0000, v213
	v_lshlrev_b32_e32 v30, 16, v214
	v_and_b32_e32 v31, 0xffff0000, v214
	v_lshlrev_b32_e32 v32, 16, v215
	v_and_b32_e32 v33, 0xffff0000, v215
	v_pk_fma_f32 v[24:25], v[24:25], 0.5, v[28:29] op_sel_hi:[1,0,1]
	v_pk_fma_f32 v[22:23], v[22:23], 0.5, v[26:27] op_sel_hi:[1,0,1]
	v_pk_fma_f32 v[26:27], v[20:21], 0.5, v[32:33] op_sel_hi:[1,0,1]
	v_pk_fma_f32 v[28:29], v[18:19], 0.5, v[30:31] op_sel_hi:[1,0,1]
	v_cvt_pk_bf16_f32 v18, v22, v23
	v_cvt_pk_bf16_f32 v19, v24, v25
	v_cvt_pk_bf16_f32 v20, v28, v29
	v_cvt_pk_bf16_f32 v21, v26, v27
	global_store_dwordx4 v[38:39], v[18:21], off offset:256
	s_nop 1
	v_mul_f32_e32 v18, v23, v23
	v_mul_f32_e32 v19, v25, v25
	v_fmac_f32_e32 v18, v22, v22
	v_fmac_f32_e32 v19, v24, v24
	v_add_f32_e32 v18, v18, v19
	v_mul_f32_e32 v19, v29, v29
	v_fmac_f32_e32 v19, v28, v28
	v_add_f32_e32 v18, v19, v18
	v_mul_f32_e32 v19, v27, v27
	v_fmac_f32_e32 v19, v26, v26
	v_add_f32_e32 v18, v19, v18
	v_add_f32_e32 v18, v34, v18
	v_mov_b32_e32 v19, v18
	s_nop 1
	v_permlane32_swap_b32_e32 v18, v19
	v_add_f32_e32 v18, v18, v19
	v_mov_b32_e32 v19, v18
	s_nop 1
	v_permlane16_swap_b32_e32 v18, v19
	s_and_saveexec_b64 s[56:57], vcc
	s_cbranch_execz .LBB0_2099
	v_lshlrev_b64 v[20:21], 6, v[94:95]
	v_lshl_add_u64 v[20:21], s[12:13], 0, v[20:21]
	v_lshl_add_u64 v[20:21], s[52:53], 2, v[20:21]
	s_lshl_b32 s72, s47, 2
	s_mov_b32 s73, s19
	v_lshl_add_u64 v[20:21], v[20:21], 0, s[72:73]
	v_add_f32_e32 v18, v18, v19
	global_store_dword v[20:21], v18, off
.LBB0_2099:
	s_or_b64 exec, exec, s[56:57]
	s_waitcnt vmcnt(7)
	v_lshlrev_b32_e32 v20, 16, v221
	v_and_b32_e32 v21, 0xffff0000, v221
	v_lshlrev_b32_e32 v22, 16, v222
	v_and_b32_e32 v23, 0xffff0000, v222
	v_pk_fma_f32 v[16:17], v[16:17], 0.5, v[20:21] op_sel_hi:[1,0,1]
	v_pk_fma_f32 v[20:21], v[10:11], 0.5, v[22:23] op_sel_hi:[1,0,1]
	v_lshl_add_u64 v[22:23], s[10:11], 0, v[92:93]
	v_lshlrev_b32_e32 v18, 16, v220
	v_and_b32_e32 v19, 0xffff0000, v220
	v_lshlrev_b32_e32 v24, 16, v223
	v_and_b32_e32 v25, 0xffff0000, v223
	v_lshl_add_u64 v[22:23], s[54:55], 1, v[22:23]
	v_pk_fma_f32 v[14:15], v[14:15], 0.5, v[18:19] op_sel_hi:[1,0,1]
	v_pk_fma_f32 v[18:19], v[12:13], 0.5, v[24:25] op_sel_hi:[1,0,1]
	v_lshl_add_u64 v[22:23], v[22:23], 0, s[18:19]
	v_cvt_pk_bf16_f32 v10, v14, v15
	v_cvt_pk_bf16_f32 v11, v16, v17
	v_cvt_pk_bf16_f32 v12, v20, v21
	v_cvt_pk_bf16_f32 v13, v18, v19
	v_lshl_add_u64 v[22:23], v[22:23], 0, v[0:1]
	global_store_dwordx4 v[22:23], v[10:13], off
	v_mul_f32_e32 v0, v15, v15
	v_fmac_f32_e32 v0, v14, v14
	v_mul_f32_e32 v10, v17, v17
	v_fmac_f32_e32 v10, v16, v16
	v_add_f32_e32 v0, v0, v10
	v_mul_f32_e32 v10, v21, v21
	v_fmac_f32_e32 v10, v20, v20
	v_add_f32_e32 v0, v10, v0
	v_mul_f32_e32 v10, v19, v19
	v_fmac_f32_e32 v10, v18, v18
	v_add_f32_e32 v0, v10, v0
	s_waitcnt vmcnt(7)
	v_lshlrev_b32_e32 v10, 16, v238
	v_and_b32_e32 v11, 0xffff0000, v238
	v_lshlrev_b32_e32 v12, 16, v239
	v_and_b32_e32 v13, 0xffff0000, v239
	v_lshlrev_b32_e32 v14, 16, v240
	v_and_b32_e32 v15, 0xffff0000, v240
	v_lshlrev_b32_e32 v16, 16, v241
	v_and_b32_e32 v17, 0xffff0000, v241
	v_pk_fma_f32 v[8:9], v[8:9], 0.5, v[12:13] op_sel_hi:[1,0,1]
	v_pk_fma_f32 v[6:7], v[6:7], 0.5, v[10:11] op_sel_hi:[1,0,1]
	v_pk_fma_f32 v[10:11], v[4:5], 0.5, v[16:17] op_sel_hi:[1,0,1]
	v_pk_fma_f32 v[12:13], v[2:3], 0.5, v[14:15] op_sel_hi:[1,0,1]
	v_cvt_pk_bf16_f32 v2, v6, v7
	v_cvt_pk_bf16_f32 v3, v8, v9
	v_cvt_pk_bf16_f32 v4, v12, v13
	v_cvt_pk_bf16_f32 v5, v10, v11
	global_store_dwordx4 v[22:23], v[2:5], off offset:256
	s_nop 1
	v_mul_f32_e32 v2, v7, v7
	v_mul_f32_e32 v3, v9, v9
	v_fmac_f32_e32 v2, v6, v6
	v_fmac_f32_e32 v3, v8, v8
	v_add_f32_e32 v2, v2, v3
	v_mul_f32_e32 v3, v13, v13
	v_fmac_f32_e32 v3, v12, v12
	v_add_f32_e32 v2, v3, v2
	v_mul_f32_e32 v3, v11, v11
	v_fmac_f32_e32 v3, v10, v10
	v_add_f32_e32 v2, v3, v2
	v_add_f32_e32 v0, v0, v2
	v_mov_b32_e32 v2, v0
	s_nop 1
	v_permlane32_swap_b32_e32 v0, v2
	v_add_f32_e32 v0, v0, v2
	v_mov_b32_e32 v2, v0
	s_nop 1
	v_permlane16_swap_b32_e32 v0, v2
	s_and_saveexec_b64 s[54:55], vcc
	s_cbranch_execz .LBB0_2101
	v_lshlrev_b64 v[4:5], 6, v[90:91]
	v_lshl_add_u64 v[4:5], s[12:13], 0, v[4:5]
	v_lshl_add_u64 v[4:5], s[52:53], 2, v[4:5]
	s_lshl_b32 s18, s47, 2
	v_lshl_add_u64 v[4:5], v[4:5], 0, s[18:19]
	v_add_f32_e32 v0, v0, v2
	global_store_dword v[4:5], v0, off
